# counted vmcnt in MLA/GQA tile loops (keep next-tile prefetch in flight); retention readout norm-gain loads batched; P3 token transforms: loads of next token prefetched
# speedup vs baseline: 1.0139x; 1.0139x over previous
; __device__ __forceinline__ unsigned cvt_pk_bf16(float lo, float hi) { unsigned r; asm volatile("v_cvt_pk_bf16_f32 %0, %1, %2" : "=v"(r) : "v"(lo), "v"(hi)); return r; }
; __device__ __forceinline__ float bflo(unsigned w) { return __uint_as_float(w << 16); }
; __global__ void __launch_bounds__(512, 2) mega_fwd(Args a) {
;     ...
;                 for (int tk = 0; tk < 8; ++tk) {
;                     const int tl = wave * 8 + tk; const int row = r0 + tl;
;                     bf16_t* ur = U + (size_t)row * DINP;
;                     const bool isl = row < TL; const int tpos = row & 4095;
;                     const float prow = (float)(tpos >> 6), pcol = (float)(tpos & 63);
;                     {
;                         const u32x2 v = *(const u32x2*)(ur + C_CQ + 4 * lane);
;                         f32x4 x = {bflo(v.x), bfhi(v.x), bflo(v.y), bfhi(v.y)};
;                         const float rs = rsqrtf(wave_sum((x.x * x.x + x.y * x.y) + (x.z * x.z + x.w * x.w), lane) * (1.f / 256.f) + EPS);
;                         x = x * rs * gq4;
;                         u32x2 w2; w2.x = cvt_pk_bf16(x.x, x.y); w2.y = cvt_pk_bf16(x.z, x.w);
;                         *(u32x2*)(ur + C_CQ + 4 * lane) = w2;
;                     }
;                     {
;                         const unsigned v = *(const unsigned*)(ur + C_CKV + 2 * lane);
;                         float x0 = bflo(v), x1 = bfhi(v);
;                         const float rs = rsqrtf(wave_sum(x0 * x0 + x1 * x1, lane) * (1.f / 128.f) + EPS);
;                         *(unsigned*)(ur + C_CKV + 2 * lane) = cvt_pk_bf16(x0 * rs * gkv2.x, x1 * rs * gkv2.y);
;                     }
;                     {
;                         const int blk = (lane >> 3) & 1, i = lane & 7;
;                         bf16_t* p = ur + C_KPE + 16 * blk + i;
;                         const float x1 = bf1(p[0]), x2 = bf1(p[8]);
;                         kpe2 = fmaxf(kpe2, (lane < 16) ? (x1 * x1 + x2 * x2) : 0.f);
;                         if (isl && lane < 16) {
;                             const float rev = (blk ? pcol : prow) * fr8;
;                             const float cs = __builtin_amdgcn_cosf(rev), sn = __builtin_amdgcn_sinf(rev);
;                             p[0] = f2bf(x1 * cs - x2 * sn); p[8] = f2bf(x1 * sn + x2 * cs);
;                         }
.LBB0_298:
	s_add_u32 s34, s10, 0x8000000
	s_addc_u32 s35, s11, 0
	v_lshl_add_u64 v[140:141], s[34:35], 0, v[36:37]
	global_load_dwordx2 v[78:79], v[140:141], off offset:1024
	v_lshl_add_u64 v[142:143], s[10:11], 0, v[50:51]
	global_load_dword v80, v[142:143], off
	v_lshl_add_u64 v[140:141], s[34:35], 0, v[52:53]
	global_load_ushort v81, v[140:141], off offset:1808
	global_load_ushort v82, v[140:141], off offset:1792
	v_lshl_add_u64 v[142:143], s[10:11], 0, v[54:55]
	global_load_ushort v83, v[142:143], off
	global_load_ushort v84, v[142:143], off offset:-64
	global_load_ushort v85, v[142:143], off offset:32
	global_load_ushort v86, v[142:143], off offset:-32
	v_lshl_add_u64 v[140:141], s[10:11], 0, v[48:49]
	global_load_ushort v87, v[140:141], off
	global_load_ushort v88, v[140:141], off offset:-64
	global_load_ushort v89, v[140:141], off offset:32
	global_load_ushort v90, v[140:141], off offset:-32
.Lp3_tok_loop:
	s_add_u32 s28, s10, 0x1400
	s_addc_u32 s29, s11, 0
	s_add_u32 s34, s28, 0x8000000
	s_addc_u32 s35, s29, 0
	v_lshl_add_u64 v[140:141], s[34:35], 0, v[36:37]
	global_load_dwordx2 v[92:93], v[140:141], off offset:1024
	v_lshl_add_u64 v[142:143], s[28:29], 0, v[50:51]
	global_load_dword v94, v[142:143], off
	v_lshl_add_u64 v[140:141], s[34:35], 0, v[52:53]
	global_load_ushort v95, v[140:141], off offset:1808
	global_load_ushort v96, v[140:141], off offset:1792
	v_lshl_add_u64 v[142:143], s[28:29], 0, v[54:55]
	global_load_ushort v97, v[142:143], off
	global_load_ushort v98, v[142:143], off offset:-64
	global_load_ushort v99, v[142:143], off offset:32
	global_load_ushort v100, v[142:143], off offset:-32
	v_lshl_add_u64 v[140:141], s[28:29], 0, v[48:49]
	global_load_ushort v101, v[140:141], off
	global_load_ushort v102, v[140:141], off offset:-64
	global_load_ushort v103, v[140:141], off offset:32
	global_load_ushort v104, v[140:141], off offset:-32
	s_add_i32 s23, s18, s21
	s_add_i32 s22, s96, s21
	s_cmp_lt_i32 s23, 0x8000
	s_cselect_b64 s[26:27], -1, 0
	v_lshl_add_u64 v[60:61], s[10:11], 0, v[36:37]
	v_add_co_u32_e32 v60, vcc, 0x8000000, v60
	s_nop 1
	v_addc_co_u32_e32 v61, vcc, 0, v61, vcc
	s_cmp_eq_u32 s21, 0
	s_cbranch_scc1 .Lp3_wA_first
	s_waitcnt vmcnt(22)
	s_branch .Lp3_wA_done
.Lp3_wA_first:
	s_waitcnt vmcnt(12)
.Lp3_wA_done:
	v_lshlrev_b32_e32 v65, 16, v79
	v_lshlrev_b32_e32 v64, 16, v78
	v_and_b32_e32 v63, 0xffff0000, v79
	v_and_b32_e32 v62, 0xffff0000, v78
	v_pk_mul_f32 v[66:67], v[62:63], v[62:63]
	v_mov_b32_e32 v68, v64
	v_pk_fma_f32 v[66:67], v[64:65], v[64:65], v[66:67]
	v_mov_b32_e32 v69, v62
	v_add_f32_e32 v57, v66, v67
	ds_bpermute_b32 v59, v109, v57
	v_mov_b32_e32 v62, v65
	v_lshl_add_u64 v[66:67], s[10:11], 0, v[50:51]
	s_waitcnt lgkmcnt(0)
	v_add_f32_e32 v57, v57, v59
	ds_bpermute_b32 v59, v110, v57
	s_waitcnt lgkmcnt(0)
	v_add_f32_e32 v57, v57, v59
	ds_bpermute_b32 v59, v111, v57
	s_waitcnt lgkmcnt(0)
	v_add_f32_e32 v57, v57, v59
	ds_bpermute_b32 v59, v112, v57
	s_waitcnt lgkmcnt(0)
	v_add_f32_e32 v57, v57, v59
	ds_bpermute_b32 v59, v113, v57
	s_waitcnt lgkmcnt(0)
	v_add_f32_e32 v57, v57, v59
	ds_bpermute_b32 v59, v114, v57
	s_waitcnt lgkmcnt(0)
	v_add_f32_e32 v57, v57, v59
	v_fmamk_f32 v57, v57, 0x3b800000, v205
	v_mul_f32_e32 v59, 0x4b800000, v57
	v_cmp_gt_f32_e32 vcc, s2, v57
	s_nop 1
	v_cndmask_b32_e32 v57, v57, v59, vcc
	v_rsq_f32_e32 v57, v57
	s_nop 0
	v_mul_f32_e32 v59, 0x45800000, v57
	v_cndmask_b32_e32 v64, v57, v59, vcc
	v_pk_mul_f32 v[68:69], v[64:65], v[68:69] op_sel_hi:[0,1]
	v_pk_mul_f32 v[62:63], v[64:65], v[62:63] op_sel_hi:[0,1]
	v_pk_mul_f32 v[64:65], v[8:9], v[68:69]
	v_pk_mul_f32 v[62:63], v[10:11], v[62:63]
	v_cvt_pk_bf16_f32 v64, v64, v65
	s_nop 0
	v_cvt_pk_bf16_f32 v65, v62, v63
	global_store_dwordx2 v[60:61], v[64:65], off offset:1024
	v_lshlrev_b32_e32 v60, 16, v80
	v_and_b32_e32 v61, 0xffff0000, v80
	v_pk_mul_f32 v[62:63], v[60:61], v[60:61]
	s_nop 0
	v_add_f32_e32 v57, v62, v63
	ds_bpermute_b32 v59, v109, v57
	v_lshl_add_u64 v[62:63], s[10:11], 0, v[52:53]
	s_waitcnt lgkmcnt(0)
	v_add_f32_e32 v57, v57, v59
	ds_bpermute_b32 v59, v110, v57
	s_mov_b64 vcc, s[26:27]
	s_waitcnt lgkmcnt(0)
	v_add_f32_e32 v57, v57, v59
	ds_bpermute_b32 v59, v111, v57
	s_and_b64 s[12:13], s[40:41], vcc
	s_waitcnt lgkmcnt(0)
	v_add_f32_e32 v57, v57, v59
	ds_bpermute_b32 v59, v112, v57
	s_waitcnt lgkmcnt(0)
	v_add_f32_e32 v57, v57, v59
	ds_bpermute_b32 v59, v113, v57
	s_waitcnt lgkmcnt(0)
	v_add_f32_e32 v57, v57, v59
	ds_bpermute_b32 v59, v114, v57
	s_waitcnt lgkmcnt(0)
	v_add_f32_e32 v57, v57, v59
	v_fmamk_f32 v57, v57, 0x3c000000, v205
	v_mul_f32_e32 v59, 0x4b800000, v57
	v_cmp_gt_f32_e64 s[0:1], s2, v57
	s_nop 1
	v_cndmask_b32_e64 v57, v57, v59, s[0:1]
	v_rsq_f32_e32 v57, v57
	s_nop 0
	v_mul_f32_e32 v59, 0x45800000, v57
	v_cndmask_b32_e64 v57, v57, v59, s[0:1]
	v_mul_f32_e32 v59, v57, v60
	v_mul_f32_e32 v57, v57, v61
	v_mul_f32_e32 v59, v34, v59
	v_mul_f32_e32 v57, v35, v57
	v_cvt_pk_bf16_f32 v60, v59, v57
	v_cvt_f32_u32_e32 v59, s22
	s_bfe_u32 s0, s23, 0x60006
	v_cvt_f32_ubyte0_e32 v57, s0
	global_store_dword v[66:67], v60, off
	v_lshlrev_b32_e32 v61, 16, v81
	v_lshlrev_b32_e32 v60, 16, v82
	s_and_saveexec_b64 s[0:1], s[12:13]
	s_cbranch_execz .Lp3_kpe_skip_a
	v_cndmask_b32_e64 v64, v59, v57, s[42:43]
	v_mul_f32_e32 v64, v23, v64
	v_sin_f32_e32 v66, v64
	v_cos_f32_e32 v67, v64
	v_lshl_add_u64 v[64:65], v[62:63], 0, s[82:83]
	s_mov_b64 s[12:13], 0x8000710
	v_mul_f32_e32 v68, v66, v61
	v_fma_f32 v68, v67, v60, -v68
	v_cvt_pk_bf16_f32 v68, v68, v145
	global_store_short v[64:65], v68, off
	v_mul_f32_e32 v64, v67, v61
	v_lshl_add_u64 v[62:63], v[62:63], 0, s[12:13]
	v_fmac_f32_e32 v64, v66, v60
	v_cvt_pk_bf16_f32 v64, v64, v145
	global_store_short v[62:63], v64, off
; __device__ __forceinline__ float bf1(bf16_t h) { return __uint_as_float(((unsigned)h) << 16); }
; __device__ __forceinline__ bf16_t f2bf(float f) { return (bf16_t)(cvt_pk_bf16(f, 0.f) & 0xffffu); }
; __global__ void __launch_bounds__(512, 2) mega_fwd(Args a) {
;     ...
;                         const int blk = (lane >> 3) & 1, i = lane & 7;
;                         bf16_t* p = ur + C_KPE + 16 * blk + i;
;                         const float x1 = bf1(p[0]), x2 = bf1(p[8]);
;                         kpe2 = fmaxf(kpe2, (lane < 16) ? (x1 * x1 + x2 * x2) : 0.f);
;                         if (isl && lane < 16) {
;                             const float rev = (blk ? pcol : prow) * fr8;
;                             const float cs = __builtin_amdgcn_cosf(rev), sn = __builtin_amdgcn_sinf(rev);
;                             p[0] = f2bf(x1 * cs - x2 * sn); p[8] = f2bf(x1 * sn + x2 * cs);
;                         }
;                     }
; #pragma unroll
;                     for (int pass = 0; pass < 2; ++pass) {
;                         const int hd = lane >> 4;
;                         const bool act = (pass == 0) || (lane < 32);
;                         bf16_t* p = ur + (pass == 0 ? C_GQ : C_GK) + (act ? hd : 0) * 64 + i16;
;                         float x0 = bf1(p[0]), x1 = bf1(p[16]), x2 = bf1(p[32]), x3 = bf1(p[48]);
;                         const float rs = rsqrtf(sum16((x0 * x0 + x1 * x1) + (x2 * x2 + x3 * x3), lane) * (1.f / 64.f) + EPS);
;                         if (pass == 0) { const float rq = rs * (0.125f * LOG2E); x0 *= rq * gg_q[0]; x1 *= rq * gg_q[1]; x2 *= rq * gg_q[2]; x3 *= rq * gg_q[3]; }
;                         else { x0 *= rs * gg_k[0]; x1 *= rs * gg_k[1]; x2 *= rs * gg_k[2]; x3 *= rs * gg_k[3]; }
;                         if (isl) {
;                             const float rr = prow * fr16, rc = pcol * fr16;
;                             const float c0 = __builtin_amdgcn_cosf(rr), s0 = __builtin_amdgcn_sinf(rr), c1 = __builtin_amdgcn_cosf(rc), s1 = __builtin_amdgcn_sinf(rc);
;                             const float y0 = x0 * c0 - x1 * s0, y1 = x0 * s0 + x1 * c0, y2 = x2 * c1 - x3 * s1, y3 = x2 * s1 + x3 * c1;
;                             x0 = y0; x1 = y1; x2 = y2; x3 = y3;
;                         }
;                         if (act) { p[0] = f2bf(x0); p[16] = f2bf(x1); p[32] = f2bf(x2); p[48] = f2bf(x3); }
;                     }
.Lp3_kpe_skip_a:
	s_or_b64 exec, exec, s[0:1]
	v_mul_f32_e32 v74, v60, v60
	v_fmac_f32_e32 v74, v61, v61
	v_cndmask_b32_e64 v74, 0, v74, s[40:41]
	v_max_f32_e32 v17, v17, v74
	v_mul_f32_e32 v57, v19, v57
	v_mul_f32_e32 v59, v19, v59
	v_lshl_add_u64 v[66:67], s[10:11], 0, v[54:55]
	v_cos_f32_e32 v63, v57
	v_sin_f32_e32 v65, v57
	v_cos_f32_e32 v62, v59
	v_sin_f32_e32 v64, v59
	v_lshlrev_b32_e32 v68, 16, v83
	v_lshlrev_b32_e32 v69, 16, v84
	v_lshlrev_b32_e32 v70, 16, v85
	v_lshlrev_b32_e32 v71, 16, v86
	v_pk_mul_f32 v[72:73], v[70:71], v[70:71]
	s_nop 0
	v_pk_fma_f32 v[72:73], v[68:69], v[68:69], v[72:73]
	s_nop 0
	v_add_f32_e32 v57, v73, v72
	ds_bpermute_b32 v59, v109, v57
	s_waitcnt lgkmcnt(0)
	v_add_f32_e32 v57, v57, v59
	ds_bpermute_b32 v59, v110, v57
	s_waitcnt lgkmcnt(0)
	v_add_f32_e32 v57, v57, v59
	ds_bpermute_b32 v59, v111, v57
	s_waitcnt lgkmcnt(0)
	v_add_f32_e32 v57, v57, v59
	ds_bpermute_b32 v59, v112, v57
	s_waitcnt lgkmcnt(0)
	v_add_f32_e32 v57, v57, v59
	v_fmamk_f32 v57, v57, 0x3c800000, v205
	v_cmp_gt_f32_e64 s[0:1], s2, v57
	v_mul_f32_e32 v59, 0x4b800000, v57
	s_nop 0
	v_cndmask_b32_e64 v57, v57, v59, s[0:1]
	v_rsq_f32_e32 v57, v57
	s_nop 0
	v_mul_f32_e32 v59, 0x45800000, v57
	v_cndmask_b32_e64 v57, v57, v59, s[0:1]
	v_mul_f32_e32 v72, 0x3e38aa3b, v57
	v_pk_mul_f32 v[74:75], v[28:29], v[72:73] op_sel_hi:[1,0]
	v_pk_mul_f32 v[72:73], v[26:27], v[72:73] op_sel_hi:[1,0]
	v_pk_mul_f32 v[70:71], v[74:75], v[70:71]
	v_pk_mul_f32 v[68:69], v[72:73], v[68:69]
	v_pk_mul_f32 v[74:75], v[64:65], v[70:71]
	v_pk_mul_f32 v[72:73], v[64:65], v[68:69]
	v_pk_fma_f32 v[74:75], v[62:63], v[68:69], v[74:75] neg_lo:[0,0,1] neg_hi:[0,0,1]
	v_pk_fma_f32 v[72:73], v[62:63], v[70:71], v[72:73]
	v_cndmask_b32_e32 v69, v69, v75, vcc
	v_cndmask_b32_e32 v59, v71, v73, vcc
	v_cndmask_b32_e32 v57, v70, v72, vcc
	v_cvt_pk_bf16_f32 v69, v69, v145
	global_store_short v[66:67], v69, off offset:-64
	v_cvt_pk_bf16_f32 v59, v59, v145
	v_cndmask_b32_e32 v68, v68, v74, vcc
	global_store_short v[66:67], v59, off offset:-32
	v_cvt_pk_bf16_f32 v59, v68, v145
	global_store_short v[66:67], v59, off
	v_cvt_pk_bf16_f32 v57, v57, v145
	global_store_short v[66:67], v57, off offset:32
	v_lshl_add_u64 v[66:67], s[10:11], 0, v[48:49]
	v_lshlrev_b32_e32 v68, 16, v87
	v_lshlrev_b32_e32 v69, 16, v88
	v_lshlrev_b32_e32 v70, 16, v89
	v_lshlrev_b32_e32 v71, 16, v90
	v_pk_mul_f32 v[72:73], v[70:71], v[70:71]
	s_nop 0
	v_pk_fma_f32 v[72:73], v[68:69], v[68:69], v[72:73]
	s_nop 0
	v_add_f32_e32 v57, v73, v72
	ds_bpermute_b32 v59, v109, v57
	s_waitcnt lgkmcnt(0)
	v_add_f32_e32 v57, v57, v59
	ds_bpermute_b32 v59, v110, v57
	s_waitcnt lgkmcnt(0)
	v_add_f32_e32 v57, v57, v59
	ds_bpermute_b32 v59, v111, v57
	s_waitcnt lgkmcnt(0)
	v_add_f32_e32 v57, v57, v59
	ds_bpermute_b32 v59, v112, v57
	s_waitcnt lgkmcnt(0)
	v_add_f32_e32 v57, v57, v59
	s_and_saveexec_b64 s[12:13], s[70:71]
	s_cbranch_execz .Lp3_gk_skip_a
	v_fmamk_f32 v57, v57, 0x3c800000, v205
	v_mul_f32_e32 v59, 0x4b800000, v57
	v_cmp_gt_f32_e64 s[0:1], s2, v57
	s_nop 1
	v_cndmask_b32_e64 v57, v57, v59, s[0:1]
	v_rsq_f32_e32 v57, v57
	s_nop 0
	v_mul_f32_e32 v59, 0x45800000, v57
	v_cndmask_b32_e64 v72, v57, v59, s[0:1]
	v_pk_mul_f32 v[74:75], v[32:33], v[72:73] op_sel_hi:[1,0]
	v_pk_mul_f32 v[72:73], v[30:31], v[72:73] op_sel_hi:[1,0]
	v_pk_mul_f32 v[70:71], v[74:75], v[70:71]
	v_pk_mul_f32 v[68:69], v[72:73], v[68:69]
	s_nop 0
	v_pk_mul_f32 v[72:73], v[64:65], v[68:69]
	v_pk_mul_f32 v[64:65], v[64:65], v[70:71]
	s_nop 0
	v_pk_fma_f32 v[64:65], v[62:63], v[68:69], v[64:65] neg_lo:[0,0,1] neg_hi:[0,0,1]
	v_pk_fma_f32 v[62:63], v[62:63], v[70:71], v[72:73]
	s_nop 0
	v_cndmask_b32_e32 v59, v71, v63, vcc
	v_cndmask_b32_e32 v63, v69, v65, vcc
	v_cndmask_b32_e32 v57, v70, v62, vcc
	v_cvt_pk_bf16_f32 v63, v63, v145
	global_store_short v[66:67], v63, off offset:-64
	v_cvt_pk_bf16_f32 v59, v59, v145
	v_cndmask_b32_e32 v62, v68, v64, vcc
	global_store_short v[66:67], v59, off offset:-32
	v_cvt_pk_bf16_f32 v59, v62, v145
	global_store_short v[66:67], v59, off
	v_cvt_pk_bf16_f32 v57, v57, v145
	global_store_short v[66:67], v57, off offset:32
.Lp3_gk_skip_a:
	s_or_b64 exec, exec, s[12:13]
	s_cmp_ge_u32 s21, 6
	s_cbranch_scc1 .Lp3_no_pf
	s_add_u32 s30, s10, 0x2800
	s_addc_u32 s31, s11, 0
	s_add_u32 s34, s30, 0x8000000
	s_addc_u32 s35, s31, 0
	v_lshl_add_u64 v[140:141], s[34:35], 0, v[36:37]
	global_load_dwordx2 v[78:79], v[140:141], off offset:1024
	v_lshl_add_u64 v[142:143], s[30:31], 0, v[50:51]
	global_load_dword v80, v[142:143], off
	v_lshl_add_u64 v[140:141], s[34:35], 0, v[52:53]
	global_load_ushort v81, v[140:141], off offset:1808
	global_load_ushort v82, v[140:141], off offset:1792
	v_lshl_add_u64 v[142:143], s[30:31], 0, v[54:55]
	global_load_ushort v83, v[142:143], off
	global_load_ushort v84, v[142:143], off offset:-64
	global_load_ushort v85, v[142:143], off offset:32
	global_load_ushort v86, v[142:143], off offset:-32
	v_lshl_add_u64 v[140:141], s[30:31], 0, v[48:49]
	global_load_ushort v87, v[140:141], off
	global_load_ushort v88, v[140:141], off offset:-64
	global_load_ushort v89, v[140:141], off offset:32
	global_load_ushort v90, v[140:141], off offset:-32
	s_waitcnt vmcnt(22)
	s_branch .Lp3_wB_done
.Lp3_no_pf:
	s_waitcnt vmcnt(10)
; __device__ __forceinline__ unsigned cvt_pk_bf16(float lo, float hi) { unsigned r; asm volatile("v_cvt_pk_bf16_f32 %0, %1, %2" : "=v"(r) : "v"(lo), "v"(hi)); return r; }
; __device__ __forceinline__ float bflo(unsigned w) { return __uint_as_float(w << 16); }
; __device__ __forceinline__ float bfhi(unsigned w) { return __uint_as_float(w & 0xffff0000u); }
; __global__ void __launch_bounds__(512, 2) mega_fwd(Args a) {
;     ...
;                     const int tl = wave * 8 + tk; const int row = r0 + tl;
;                     bf16_t* ur = U + (size_t)row * DINP;
;                     const bool isl = row < TL; const int tpos = row & 4095;
;                     const float prow = (float)(tpos >> 6), pcol = (float)(tpos & 63);
;                     {
;                         const u32x2 v = *(const u32x2*)(ur + C_CQ + 4 * lane);
;                         f32x4 x = {bflo(v.x), bfhi(v.x), bflo(v.y), bfhi(v.y)};
;                         const float rs = rsqrtf(wave_sum((x.x * x.x + x.y * x.y) + (x.z * x.z + x.w * x.w), lane) * (1.f / 256.f) + EPS);
;                         x = x * rs * gq4;
;                         u32x2 w2; w2.x = cvt_pk_bf16(x.x, x.y); w2.y = cvt_pk_bf16(x.z, x.w);
;                         *(u32x2*)(ur + C_CQ + 4 * lane) = w2;
;                     }
;                     {
;                         const unsigned v = *(const unsigned*)(ur + C_CKV + 2 * lane);
;                         float x0 = bflo(v), x1 = bfhi(v);
;                         const float rs = rsqrtf(wave_sum(x0 * x0 + x1 * x1, lane) * (1.f / 128.f) + EPS);
;                         *(unsigned*)(ur + C_CKV + 2 * lane) = cvt_pk_bf16(x0 * rs * gkv2.x, x1 * rs * gkv2.y);
;                     }
;                     {
;                         const int blk = (lane >> 3) & 1, i = lane & 7;
;                         bf16_t* p = ur + C_KPE + 16 * blk + i;
;                         const float x1 = bf1(p[0]), x2 = bf1(p[8]);
;                         kpe2 = fmaxf(kpe2, (lane < 16) ? (x1 * x1 + x2 * x2) : 0.f);
;                         if (isl && lane < 16) {
;                             const float rev = (blk ? pcol : prow) * fr8;
;                             const float cs = __builtin_amdgcn_cosf(rev), sn = __builtin_amdgcn_sinf(rev);
;                             p[0] = f2bf(x1 * cs - x2 * sn); p[8] = f2bf(x1 * sn + x2 * cs);
;                         }
.Lp3_wB_done:
	s_add_i32 s23, s18, s21
	s_add_i32 s22, s96, s21
	s_add_i32 s23, s23, 1
	s_add_i32 s22, s22, 1
	s_cmp_lt_i32 s23, 0x8000
	s_cselect_b64 s[26:27], -1, 0
	v_lshl_add_u64 v[60:61], s[28:29], 0, v[36:37]
	v_add_co_u32_e32 v60, vcc, 0x8000000, v60
	s_nop 1
	v_addc_co_u32_e32 v61, vcc, 0, v61, vcc
	v_lshlrev_b32_e32 v65, 16, v93
	v_lshlrev_b32_e32 v64, 16, v92
	v_and_b32_e32 v63, 0xffff0000, v93
	v_and_b32_e32 v62, 0xffff0000, v92
	v_pk_mul_f32 v[66:67], v[62:63], v[62:63]
	v_mov_b32_e32 v68, v64
	v_pk_fma_f32 v[66:67], v[64:65], v[64:65], v[66:67]
	v_mov_b32_e32 v69, v62
	v_add_f32_e32 v57, v66, v67
	ds_bpermute_b32 v59, v109, v57
	v_mov_b32_e32 v62, v65
	v_lshl_add_u64 v[66:67], s[28:29], 0, v[50:51]
	s_waitcnt lgkmcnt(0)
	v_add_f32_e32 v57, v57, v59
	ds_bpermute_b32 v59, v110, v57
	s_waitcnt lgkmcnt(0)
	v_add_f32_e32 v57, v57, v59
	ds_bpermute_b32 v59, v111, v57
	s_waitcnt lgkmcnt(0)
	v_add_f32_e32 v57, v57, v59
	ds_bpermute_b32 v59, v112, v57
	s_waitcnt lgkmcnt(0)
	v_add_f32_e32 v57, v57, v59
	ds_bpermute_b32 v59, v113, v57
	s_waitcnt lgkmcnt(0)
	v_add_f32_e32 v57, v57, v59
	ds_bpermute_b32 v59, v114, v57
	s_waitcnt lgkmcnt(0)
	v_add_f32_e32 v57, v57, v59
	v_fmamk_f32 v57, v57, 0x3b800000, v205
	v_mul_f32_e32 v59, 0x4b800000, v57
	v_cmp_gt_f32_e32 vcc, s2, v57
	s_nop 1
	v_cndmask_b32_e32 v57, v57, v59, vcc
	v_rsq_f32_e32 v57, v57
	s_nop 0
	v_mul_f32_e32 v59, 0x45800000, v57
	v_cndmask_b32_e32 v64, v57, v59, vcc
	v_pk_mul_f32 v[68:69], v[64:65], v[68:69] op_sel_hi:[0,1]
	v_pk_mul_f32 v[62:63], v[64:65], v[62:63] op_sel_hi:[0,1]
	v_pk_mul_f32 v[64:65], v[8:9], v[68:69]
	v_pk_mul_f32 v[62:63], v[10:11], v[62:63]
	v_cvt_pk_bf16_f32 v64, v64, v65
	s_nop 0
	v_cvt_pk_bf16_f32 v65, v62, v63
	global_store_dwordx2 v[60:61], v[64:65], off offset:1024
	v_lshlrev_b32_e32 v60, 16, v94
	v_and_b32_e32 v61, 0xffff0000, v94
	v_pk_mul_f32 v[62:63], v[60:61], v[60:61]
	s_nop 0
	v_add_f32_e32 v57, v62, v63
	ds_bpermute_b32 v59, v109, v57
	v_lshl_add_u64 v[62:63], s[28:29], 0, v[52:53]
	s_waitcnt lgkmcnt(0)
	v_add_f32_e32 v57, v57, v59
	ds_bpermute_b32 v59, v110, v57
	s_mov_b64 vcc, s[26:27]
	s_waitcnt lgkmcnt(0)
	v_add_f32_e32 v57, v57, v59
	ds_bpermute_b32 v59, v111, v57
	s_and_b64 s[12:13], s[40:41], vcc
	s_waitcnt lgkmcnt(0)
	v_add_f32_e32 v57, v57, v59
	ds_bpermute_b32 v59, v112, v57
	s_waitcnt lgkmcnt(0)
	v_add_f32_e32 v57, v57, v59
	ds_bpermute_b32 v59, v113, v57
	s_waitcnt lgkmcnt(0)
	v_add_f32_e32 v57, v57, v59
	ds_bpermute_b32 v59, v114, v57
	s_waitcnt lgkmcnt(0)
	v_add_f32_e32 v57, v57, v59
	v_fmamk_f32 v57, v57, 0x3c000000, v205
	v_mul_f32_e32 v59, 0x4b800000, v57
	v_cmp_gt_f32_e64 s[0:1], s2, v57
	s_nop 1
	v_cndmask_b32_e64 v57, v57, v59, s[0:1]
	v_rsq_f32_e32 v57, v57
	s_nop 0
	v_mul_f32_e32 v59, 0x45800000, v57
	v_cndmask_b32_e64 v57, v57, v59, s[0:1]
	v_mul_f32_e32 v59, v57, v60
	v_mul_f32_e32 v57, v57, v61
	v_mul_f32_e32 v59, v34, v59
	v_mul_f32_e32 v57, v35, v57
	v_cvt_pk_bf16_f32 v60, v59, v57
	v_cvt_f32_u32_e32 v59, s22
	s_bfe_u32 s0, s23, 0x60006
	v_cvt_f32_ubyte0_e32 v57, s0
	global_store_dword v[66:67], v60, off
	v_lshlrev_b32_e32 v61, 16, v95
	v_lshlrev_b32_e32 v60, 16, v96
	s_and_saveexec_b64 s[0:1], s[12:13]
	s_cbranch_execz .Lp3_kpe_skip_b
	v_cndmask_b32_e64 v64, v59, v57, s[42:43]
	v_mul_f32_e32 v64, v23, v64
	v_sin_f32_e32 v66, v64
	v_cos_f32_e32 v67, v64
	v_lshl_add_u64 v[64:65], v[62:63], 0, s[82:83]
	s_mov_b64 s[12:13], 0x8000710
	v_mul_f32_e32 v68, v66, v61
	v_fma_f32 v68, v67, v60, -v68
	v_cvt_pk_bf16_f32 v68, v68, v145
	global_store_short v[64:65], v68, off
	v_mul_f32_e32 v64, v67, v61
	v_lshl_add_u64 v[62:63], v[62:63], 0, s[12:13]
	v_fmac_f32_e32 v64, v66, v60
	v_cvt_pk_bf16_f32 v64, v64, v145
	global_store_short v[62:63], v64, off
; __device__ __forceinline__ float bf1(bf16_t h) { return __uint_as_float(((unsigned)h) << 16); }
; __device__ __forceinline__ bf16_t f2bf(float f) { return (bf16_t)(cvt_pk_bf16(f, 0.f) & 0xffffu); }
; __global__ void __launch_bounds__(512, 2) mega_fwd(Args a) {
;     ...
;                         const float x1 = bf1(p[0]), x2 = bf1(p[8]);
;                         kpe2 = fmaxf(kpe2, (lane < 16) ? (x1 * x1 + x2 * x2) : 0.f);
;                         if (isl && lane < 16) {
;                             const float rev = (blk ? pcol : prow) * fr8;
;                             const float cs = __builtin_amdgcn_cosf(rev), sn = __builtin_amdgcn_sinf(rev);
;                             p[0] = f2bf(x1 * cs - x2 * sn); p[8] = f2bf(x1 * sn + x2 * cs);
;                         }
;                     }
; #pragma unroll
;                     for (int pass = 0; pass < 2; ++pass) {
;                         const int hd = lane >> 4;
;                         const bool act = (pass == 0) || (lane < 32);
;                         bf16_t* p = ur + (pass == 0 ? C_GQ : C_GK) + (act ? hd : 0) * 64 + i16;
;                         float x0 = bf1(p[0]), x1 = bf1(p[16]), x2 = bf1(p[32]), x3 = bf1(p[48]);
;                         const float rs = rsqrtf(sum16((x0 * x0 + x1 * x1) + (x2 * x2 + x3 * x3), lane) * (1.f / 64.f) + EPS);
;                         if (pass == 0) { const float rq = rs * (0.125f * LOG2E); x0 *= rq * gg_q[0]; x1 *= rq * gg_q[1]; x2 *= rq * gg_q[2]; x3 *= rq * gg_q[3]; }
;                         else { x0 *= rs * gg_k[0]; x1 *= rs * gg_k[1]; x2 *= rs * gg_k[2]; x3 *= rs * gg_k[3]; }
;                         if (isl) {
;                             const float rr = prow * fr16, rc = pcol * fr16;
;                             const float c0 = __builtin_amdgcn_cosf(rr), s0 = __builtin_amdgcn_sinf(rr), c1 = __builtin_amdgcn_cosf(rc), s1 = __builtin_amdgcn_sinf(rc);
;                             const float y0 = x0 * c0 - x1 * s0, y1 = x0 * s0 + x1 * c0, y2 = x2 * c1 - x3 * s1, y3 = x2 * s1 + x3 * c1;
;                             x0 = y0; x1 = y1; x2 = y2; x3 = y3;
;                         }
;                         if (act) { p[0] = f2bf(x0); p[16] = f2bf(x1); p[32] = f2bf(x2); p[48] = f2bf(x3); }
;                     }
;                 }
.Lp3_kpe_skip_b:
	s_or_b64 exec, exec, s[0:1]
	v_mul_f32_e32 v74, v60, v60
	v_fmac_f32_e32 v74, v61, v61
	v_cndmask_b32_e64 v74, 0, v74, s[40:41]
	v_max_f32_e32 v17, v17, v74
	v_mul_f32_e32 v57, v19, v57
	v_mul_f32_e32 v59, v19, v59
	v_lshl_add_u64 v[66:67], s[28:29], 0, v[54:55]
	v_cos_f32_e32 v63, v57
	v_sin_f32_e32 v65, v57
	v_cos_f32_e32 v62, v59
	v_sin_f32_e32 v64, v59
	v_lshlrev_b32_e32 v68, 16, v97
	v_lshlrev_b32_e32 v69, 16, v98
	v_lshlrev_b32_e32 v70, 16, v99
	v_lshlrev_b32_e32 v71, 16, v100
	v_pk_mul_f32 v[72:73], v[70:71], v[70:71]
	s_nop 0
	v_pk_fma_f32 v[72:73], v[68:69], v[68:69], v[72:73]
	s_nop 0
	v_add_f32_e32 v57, v73, v72
	ds_bpermute_b32 v59, v109, v57
	s_waitcnt lgkmcnt(0)
	v_add_f32_e32 v57, v57, v59
	ds_bpermute_b32 v59, v110, v57
	s_waitcnt lgkmcnt(0)
	v_add_f32_e32 v57, v57, v59
	ds_bpermute_b32 v59, v111, v57
	s_waitcnt lgkmcnt(0)
	v_add_f32_e32 v57, v57, v59
	ds_bpermute_b32 v59, v112, v57
	s_waitcnt lgkmcnt(0)
	v_add_f32_e32 v57, v57, v59
	v_fmamk_f32 v57, v57, 0x3c800000, v205
	v_cmp_gt_f32_e64 s[0:1], s2, v57
	v_mul_f32_e32 v59, 0x4b800000, v57
	s_nop 0
	v_cndmask_b32_e64 v57, v57, v59, s[0:1]
	v_rsq_f32_e32 v57, v57
	s_nop 0
	v_mul_f32_e32 v59, 0x45800000, v57
	v_cndmask_b32_e64 v57, v57, v59, s[0:1]
	v_mul_f32_e32 v72, 0x3e38aa3b, v57
	v_pk_mul_f32 v[74:75], v[28:29], v[72:73] op_sel_hi:[1,0]
	v_pk_mul_f32 v[72:73], v[26:27], v[72:73] op_sel_hi:[1,0]
	v_pk_mul_f32 v[70:71], v[74:75], v[70:71]
	v_pk_mul_f32 v[68:69], v[72:73], v[68:69]
	v_pk_mul_f32 v[74:75], v[64:65], v[70:71]
	v_pk_mul_f32 v[72:73], v[64:65], v[68:69]
	v_pk_fma_f32 v[74:75], v[62:63], v[68:69], v[74:75] neg_lo:[0,0,1] neg_hi:[0,0,1]
	v_pk_fma_f32 v[72:73], v[62:63], v[70:71], v[72:73]
	v_cndmask_b32_e32 v69, v69, v75, vcc
	v_cndmask_b32_e32 v59, v71, v73, vcc
	v_cndmask_b32_e32 v57, v70, v72, vcc
	v_cvt_pk_bf16_f32 v69, v69, v145
	global_store_short v[66:67], v69, off offset:-64
	v_cvt_pk_bf16_f32 v59, v59, v145
	v_cndmask_b32_e32 v68, v68, v74, vcc
	global_store_short v[66:67], v59, off offset:-32
	v_cvt_pk_bf16_f32 v59, v68, v145
	global_store_short v[66:67], v59, off
	v_cvt_pk_bf16_f32 v57, v57, v145
	global_store_short v[66:67], v57, off offset:32
	v_lshl_add_u64 v[66:67], s[28:29], 0, v[48:49]
	v_lshlrev_b32_e32 v68, 16, v101
	v_lshlrev_b32_e32 v69, 16, v102
	v_lshlrev_b32_e32 v70, 16, v103
	v_lshlrev_b32_e32 v71, 16, v104
	v_pk_mul_f32 v[72:73], v[70:71], v[70:71]
	s_nop 0
	v_pk_fma_f32 v[72:73], v[68:69], v[68:69], v[72:73]
	s_nop 0
	v_add_f32_e32 v57, v73, v72
	ds_bpermute_b32 v59, v109, v57
	s_waitcnt lgkmcnt(0)
	v_add_f32_e32 v57, v57, v59
	ds_bpermute_b32 v59, v110, v57
	s_waitcnt lgkmcnt(0)
	v_add_f32_e32 v57, v57, v59
	ds_bpermute_b32 v59, v111, v57
	s_waitcnt lgkmcnt(0)
	v_add_f32_e32 v57, v57, v59
	ds_bpermute_b32 v59, v112, v57
	s_waitcnt lgkmcnt(0)
	v_add_f32_e32 v57, v57, v59
	s_and_saveexec_b64 s[12:13], s[70:71]
	s_cbranch_execz .Lp3_gk_skip_b
	v_fmamk_f32 v57, v57, 0x3c800000, v205
	v_mul_f32_e32 v59, 0x4b800000, v57
	v_cmp_gt_f32_e64 s[0:1], s2, v57
	s_nop 1
	v_cndmask_b32_e64 v57, v57, v59, s[0:1]
	v_rsq_f32_e32 v57, v57
	s_nop 0
	v_mul_f32_e32 v59, 0x45800000, v57
	v_cndmask_b32_e64 v72, v57, v59, s[0:1]
	v_pk_mul_f32 v[74:75], v[32:33], v[72:73] op_sel_hi:[1,0]
	v_pk_mul_f32 v[72:73], v[30:31], v[72:73] op_sel_hi:[1,0]
	v_pk_mul_f32 v[70:71], v[74:75], v[70:71]
	v_pk_mul_f32 v[68:69], v[72:73], v[68:69]
	s_nop 0
	v_pk_mul_f32 v[72:73], v[64:65], v[68:69]
	v_pk_mul_f32 v[64:65], v[64:65], v[70:71]
	s_nop 0
	v_pk_fma_f32 v[64:65], v[62:63], v[68:69], v[64:65] neg_lo:[0,0,1] neg_hi:[0,0,1]
	v_pk_fma_f32 v[62:63], v[62:63], v[70:71], v[72:73]
	s_nop 0
	v_cndmask_b32_e32 v59, v71, v63, vcc
	v_cndmask_b32_e32 v63, v69, v65, vcc
	v_cndmask_b32_e32 v57, v70, v62, vcc
	v_cvt_pk_bf16_f32 v63, v63, v145
	global_store_short v[66:67], v63, off offset:-64
	v_cvt_pk_bf16_f32 v59, v59, v145
	v_cndmask_b32_e32 v62, v68, v64, vcc
	global_store_short v[66:67], v59, off offset:-32
	v_cvt_pk_bf16_f32 v59, v62, v145
	global_store_short v[66:67], v59, off
	v_cvt_pk_bf16_f32 v57, v57, v145
	global_store_short v[66:67], v57, off offset:32
.Lp3_gk_skip_b:
	s_or_b64 exec, exec, s[12:13]
	s_add_i32 s21, s21, 2
	s_add_u32 s10, s10, 0x2800
	s_addc_u32 s11, s11, 0
	s_cmp_eq_u32 s21, 8
	s_cbranch_scc0 .Lp3_tok_loop

.LBB0_543:
	ds_read_b128 v[32:35], v105
	ds_read_b128 v[132:135], v105 offset:32
	ds_read_b128 v[48:51], v105 offset:6656
	ds_read_b128 v[136:139], v105 offset:6688
	ds_read_b128 v[140:143], v105 offset:64
	ds_read_b128 v[146:149], v105 offset:96
	ds_read_b128 v[152:155], v105 offset:6720
	ds_read_b128 v[156:159], v105 offset:6752
	ds_read_b128 v[160:163], v105 offset:128
	ds_read_b128 v[164:167], v105 offset:160
	ds_read_b128 v[168:171], v105 offset:6784
	ds_read_b128 v[172:175], v105 offset:6816
	s_waitcnt lgkmcnt(11)
	v_mfma_f32_32x32x16_bf16 v[32:47], v[32:35], v[64:67], 0
	s_waitcnt lgkmcnt(9)
	v_mfma_f32_32x32x16_bf16 v[48:63], v[48:51], v[64:67], 0
	v_mfma_f32_32x32x16_bf16 v[32:47], v[132:135], v[68:71], v[32:47]
	s_waitcnt lgkmcnt(8)
	v_mfma_f32_32x32x16_bf16 v[48:63], v[136:139], v[68:71], v[48:63]
	s_waitcnt lgkmcnt(7)
	v_mfma_f32_32x32x16_bf16 v[32:47], v[140:143], v[72:75], v[32:47]
	s_waitcnt lgkmcnt(5)
	v_mfma_f32_32x32x16_bf16 v[48:63], v[152:155], v[72:75], v[48:63]
	v_mfma_f32_32x32x16_bf16 v[32:47], v[146:149], v[76:79], v[32:47]
	s_waitcnt lgkmcnt(4)
	v_mfma_f32_32x32x16_bf16 v[48:63], v[156:159], v[76:79], v[48:63]
	s_waitcnt lgkmcnt(3)
	v_mfma_f32_32x32x16_bf16 v[32:47], v[160:163], v[80:83], v[32:47]
	s_waitcnt lgkmcnt(1)
	v_mfma_f32_32x32x16_bf16 v[48:63], v[168:171], v[80:83], v[48:63]
	v_mfma_f32_32x32x16_bf16 v[32:47], v[164:167], v[84:87], v[32:47]
	s_waitcnt lgkmcnt(0)
	v_mfma_f32_32x32x16_bf16 v[48:63], v[172:175], v[84:87], v[48:63]
	s_nop 9
	v_exp_f32_e32 v121, v32
	v_exp_f32_e32 v125, v33
	v_exp_f32_e32 v126, v34
	v_exp_f32_e32 v127, v35
	v_exp_f32_e32 v131, v36
	v_exp_f32_e32 v132, v37
	v_exp_f32_e32 v133, v38
	v_exp_f32_e32 v135, v48
	v_exp_f32_e32 v136, v49
	v_exp_f32_e32 v137, v50
	v_exp_f32_e32 v138, v51
	v_exp_f32_e32 v139, v52
	v_exp_f32_e32 v140, v53
	v_exp_f32_e32 v141, v54
	v_exp_f32_e32 v134, v39
	v_exp_f32_e32 v142, v55
	v_exp_f32_e32 v143, v40
	v_exp_f32_e32 v158, v56
	v_exp_f32_e32 v144, v41
	v_exp_f32_e32 v159, v57
	v_exp_f32_e32 v152, v42
	v_exp_f32_e32 v160, v58
	v_exp_f32_e32 v153, v43
	v_exp_f32_e32 v161, v59
	v_exp_f32_e32 v154, v44
	v_exp_f32_e32 v162, v60
	v_exp_f32_e32 v155, v45
	v_exp_f32_e32 v163, v61
	v_exp_f32_e32 v156, v46
	v_exp_f32_e32 v164, v62
	v_exp_f32_e32 v157, v47
	v_exp_f32_e32 v165, v63
	ds_read_b64_tr_b16 v[32:33], v218 offset:13312
	ds_read_b64_tr_b16 v[34:35], v218 offset:14336
	ds_read_b64_tr_b16 v[38:39], v218 offset:14592
	ds_read_b64_tr_b16 v[36:37], v218 offset:13568
	ds_read_b64_tr_b16 v[40:41], v218 offset:15360
	ds_read_b64_tr_b16 v[42:43], v218 offset:16384
	ds_read_b64_tr_b16 v[46:47], v218 offset:16640
	ds_read_b64_tr_b16 v[44:45], v218 offset:15616
	ds_read_b64_tr_b16 v[48:49], v218 offset:17408
	ds_read_b64_tr_b16 v[50:51], v218 offset:18432
	ds_read_b64_tr_b16 v[54:55], v218 offset:18688
	ds_read_b64_tr_b16 v[52:53], v218 offset:17664
	ds_read_b64_tr_b16 v[56:57], v218 offset:19456
	ds_read_b64_tr_b16 v[58:59], v218 offset:20480
	ds_read_b64_tr_b16 v[62:63], v218 offset:20736
	ds_read_b64_tr_b16 v[60:61], v218 offset:19712
	v_cvt_pk_bf16_f32 v146, v121, v125
	v_cvt_pk_bf16_f32 v147, v126, v127
	v_cvt_pk_bf16_f32 v148, v131, v132
	v_cvt_pk_bf16_f32 v149, v133, v134
	s_add_i32 s13, s12, 1
	s_waitcnt lgkmcnt(14)
	v_mfma_f32_32x32x16_bf16 v[16:31], v[32:35], v[146:149], v[16:31]
	v_cvt_pk_bf16_f32 v32, v135, v136
	v_cvt_pk_bf16_f32 v33, v137, v138
	v_cvt_pk_bf16_f32 v34, v139, v140
	v_cvt_pk_bf16_f32 v35, v141, v142
	s_cmp_ge_u32 s13, s31
	s_waitcnt lgkmcnt(12)
	v_mfma_f32_32x32x16_bf16 v[0:15], v[36:39], v[146:149], v[0:15]
	v_cvt_pk_bf16_f32 v36, v143, v144
	v_cvt_pk_bf16_f32 v37, v152, v153
	v_cvt_pk_bf16_f32 v38, v154, v155
	v_cvt_pk_bf16_f32 v39, v156, v157
	s_waitcnt lgkmcnt(10)
	v_mfma_f32_32x32x16_bf16 v[16:31], v[40:43], v[36:39], v[16:31]
	s_waitcnt lgkmcnt(8)
	v_mfma_f32_32x32x16_bf16 v[0:15], v[44:47], v[36:39], v[0:15]
	s_waitcnt lgkmcnt(6)
	v_mfma_f32_32x32x16_bf16 v[16:31], v[48:51], v[32:35], v[16:31]
	s_waitcnt lgkmcnt(4)
	v_mfma_f32_32x32x16_bf16 v[0:15], v[52:55], v[32:35], v[0:15]
	v_cvt_pk_bf16_f32 v32, v158, v159
	v_cvt_pk_bf16_f32 v33, v160, v161
	v_cvt_pk_bf16_f32 v34, v162, v163
	v_cvt_pk_bf16_f32 v35, v164, v165
	s_waitcnt lgkmcnt(2)
	v_mfma_f32_32x32x16_bf16 v[16:31], v[56:59], v[32:35], v[16:31]
	s_waitcnt lgkmcnt(0)
	v_mfma_f32_32x32x16_bf16 v[0:15], v[60:63], v[32:35], v[0:15]
	s_cbranch_scc1 .LBB0_545
	s_cmp_ge_u32 s11, s31
	s_cbranch_scc1 .Lmla_w0_tail
	s_waitcnt vmcnt(5)
	ds_write_b128 v220, v[96:99] offset:21504
	s_waitcnt vmcnt(4)
	ds_write_b128 v219, v[100:103] offset:34816
	s_waitcnt vmcnt(3)
	ds_write_b64 v129, v[114:115] offset:21632
	s_branch .LBB0_545
.Lmla_w0_tail:
	s_waitcnt vmcnt(2)
	ds_write_b128 v220, v[96:99] offset:21504
	s_waitcnt vmcnt(1)
	ds_write_b128 v219, v[100:103] offset:34816
	s_waitcnt vmcnt(0)
	ds_write_b64 v129, v[114:115] offset:21632

.LBB0_547:
	ds_read_b128 v[32:35], v105 offset:21504
	ds_read_b128 v[146:149], v105 offset:21536
	ds_read_b128 v[48:51], v105 offset:28160
	ds_read_b128 v[166:169], v105 offset:28192
	ds_read_b128 v[170:173], v105 offset:21568
	ds_read_b128 v[174:177], v105 offset:21600
	ds_read_b128 v[178:181], v105 offset:28224
	ds_read_b128 v[182:185], v105 offset:28256
	ds_read_b128 v[186:189], v105 offset:21632
	ds_read_b128 v[190:193], v105 offset:21664
	ds_read_b128 v[194:197], v105 offset:28288
	ds_read_b128 v[198:201], v105 offset:28320
	s_waitcnt lgkmcnt(11)
	v_mfma_f32_32x32x16_bf16 v[32:47], v[32:35], v[64:67], 0
	s_waitcnt lgkmcnt(9)
	v_mfma_f32_32x32x16_bf16 v[48:63], v[48:51], v[64:67], 0
	v_mfma_f32_32x32x16_bf16 v[32:47], v[146:149], v[68:71], v[32:47]
	s_waitcnt lgkmcnt(8)
	v_mfma_f32_32x32x16_bf16 v[48:63], v[166:169], v[68:71], v[48:63]
	s_waitcnt lgkmcnt(7)
	v_mfma_f32_32x32x16_bf16 v[32:47], v[170:173], v[72:75], v[32:47]
	s_waitcnt lgkmcnt(5)
	v_mfma_f32_32x32x16_bf16 v[48:63], v[178:181], v[72:75], v[48:63]
	v_mfma_f32_32x32x16_bf16 v[32:47], v[174:177], v[76:79], v[32:47]
	s_waitcnt lgkmcnt(4)
	v_mfma_f32_32x32x16_bf16 v[48:63], v[182:185], v[76:79], v[48:63]
	s_waitcnt lgkmcnt(3)
	v_mfma_f32_32x32x16_bf16 v[32:47], v[186:189], v[80:83], v[32:47]
	s_waitcnt lgkmcnt(1)
	v_mfma_f32_32x32x16_bf16 v[48:63], v[194:197], v[80:83], v[48:63]
	v_mfma_f32_32x32x16_bf16 v[32:47], v[190:193], v[84:87], v[32:47]
	s_waitcnt lgkmcnt(0)
	v_mfma_f32_32x32x16_bf16 v[48:63], v[198:201], v[84:87], v[48:63]
	s_nop 9
	v_exp_f32_e32 v32, v32
	v_exp_f32_e32 v33, v33
	v_exp_f32_e32 v34, v34
	v_exp_f32_e32 v35, v35
	v_exp_f32_e32 v36, v36
	v_exp_f32_e32 v37, v37
	v_exp_f32_e32 v38, v38
	v_exp_f32_e32 v48, v48
	v_exp_f32_e32 v49, v49
	v_exp_f32_e32 v50, v50
	v_exp_f32_e32 v51, v51
	v_exp_f32_e32 v52, v52
	v_exp_f32_e32 v53, v53
	v_exp_f32_e32 v54, v54
	v_exp_f32_e32 v39, v39
	v_exp_f32_e32 v55, v55
	v_exp_f32_e32 v40, v40
	v_exp_f32_e32 v56, v56
	v_exp_f32_e32 v41, v41
	v_exp_f32_e32 v57, v57
	v_exp_f32_e32 v42, v42
	v_exp_f32_e32 v58, v58
	v_exp_f32_e32 v43, v43
	v_exp_f32_e32 v59, v59
	v_exp_f32_e32 v44, v44
	v_exp_f32_e32 v60, v60
	v_exp_f32_e32 v45, v45
	v_exp_f32_e32 v61, v61
	v_exp_f32_e32 v46, v46
	v_exp_f32_e32 v62, v62
	v_exp_f32_e32 v47, v47
	v_exp_f32_e32 v63, v63
	ds_read_b64_tr_b16 v[146:147], v218 offset:34816
	ds_read_b64_tr_b16 v[148:149], v218 offset:35840
	ds_read_b64_tr_b16 v[168:169], v218 offset:36096
	ds_read_b64_tr_b16 v[166:167], v218 offset:35072
	ds_read_b64_tr_b16 v[170:171], v218 offset:36864
	ds_read_b64_tr_b16 v[172:173], v218 offset:37888
	ds_read_b64_tr_b16 v[176:177], v218 offset:38144
	ds_read_b64_tr_b16 v[174:175], v218 offset:37120
	ds_read_b64_tr_b16 v[178:179], v218 offset:38912
	ds_read_b64_tr_b16 v[180:181], v218 offset:39936
	ds_read_b64_tr_b16 v[184:185], v218 offset:40192
	ds_read_b64_tr_b16 v[182:183], v218 offset:39168
	ds_read_b64_tr_b16 v[186:187], v218 offset:40960
	ds_read_b64_tr_b16 v[188:189], v218 offset:41984
	ds_read_b64_tr_b16 v[192:193], v218 offset:42240
	ds_read_b64_tr_b16 v[190:191], v218 offset:41216
	v_cvt_pk_bf16_f32 v194, v32, v33
	v_cvt_pk_bf16_f32 v195, v34, v35
	v_cvt_pk_bf16_f32 v196, v36, v37
	v_cvt_pk_bf16_f32 v197, v38, v39
	s_andn2_b64 vcc, exec, s[8:9]
	s_waitcnt lgkmcnt(14)
	v_mfma_f32_32x32x16_bf16 v[16:31], v[146:149], v[194:197], v[16:31]
	v_cvt_pk_bf16_f32 v146, v48, v49
	v_cvt_pk_bf16_f32 v147, v50, v51
	v_cvt_pk_bf16_f32 v148, v52, v53
	v_cvt_pk_bf16_f32 v149, v54, v55
	s_waitcnt lgkmcnt(12)
	v_mfma_f32_32x32x16_bf16 v[0:15], v[166:169], v[194:197], v[0:15]
	v_cvt_pk_bf16_f32 v166, v40, v41
	v_cvt_pk_bf16_f32 v167, v42, v43
	v_cvt_pk_bf16_f32 v168, v44, v45
	v_cvt_pk_bf16_f32 v169, v46, v47
	s_waitcnt lgkmcnt(10)
	v_mfma_f32_32x32x16_bf16 v[16:31], v[170:173], v[166:169], v[16:31]
	s_waitcnt lgkmcnt(8)
	v_mfma_f32_32x32x16_bf16 v[0:15], v[174:177], v[166:169], v[0:15]
	s_waitcnt lgkmcnt(6)
	v_mfma_f32_32x32x16_bf16 v[16:31], v[178:181], v[146:149], v[16:31]
	s_waitcnt lgkmcnt(4)
	v_mfma_f32_32x32x16_bf16 v[0:15], v[182:185], v[146:149], v[0:15]
	v_cvt_pk_bf16_f32 v146, v56, v57
	v_cvt_pk_bf16_f32 v147, v58, v59
	v_cvt_pk_bf16_f32 v148, v60, v61
	v_cvt_pk_bf16_f32 v149, v62, v63
	s_waitcnt lgkmcnt(2)
	v_mfma_f32_32x32x16_bf16 v[16:31], v[186:189], v[146:149], v[16:31]
	s_waitcnt lgkmcnt(0)
	v_mfma_f32_32x32x16_bf16 v[0:15], v[190:193], v[146:149], v[0:15]
	s_cbranch_vccnz .LBB0_549
	s_add_i32 s13, s10, 2
	s_cmp_ge_u32 s11, s13
	s_cbranch_scc1 .Lmla_w1_tail
	s_waitcnt vmcnt(5)
	ds_write_b128 v220, v[88:91]
	s_waitcnt vmcnt(4)
	ds_write_b128 v219, v[92:95] offset:13312
	s_waitcnt vmcnt(3)
	ds_write_b64 v129, v[116:117] offset:128
	s_branch .LBB0_549
.Lmla_w1_tail:
	s_waitcnt vmcnt(2)
	ds_write_b128 v220, v[88:91]
	s_waitcnt vmcnt(1)
	ds_write_b128 v219, v[92:95] offset:13312
	s_waitcnt vmcnt(0)
	ds_write_b64 v129, v[116:117] offset:128

.LBB0_580:
	ds_read_b128 v[32:35], v194
	ds_read_b128 v[96:99], v194 offset:32
	ds_read_b128 v[36:39], v194 offset:4608
	ds_read_b128 v[104:107], v194 offset:4640
	ds_read_b128 v[114:117], v194 offset:64
	ds_read_b128 v[118:121], v194 offset:96
	ds_read_b128 v[122:125], v194 offset:4672
	ds_read_b128 v[134:137], v194 offset:4704
	ds_read_b64_tr_b16 v[138:139], v218 offset:9216
	ds_read_b64_tr_b16 v[140:141], v218 offset:10240
	ds_read_b64_tr_b16 v[148:149], v218 offset:10496
	ds_read_b64_tr_b16 v[146:147], v218 offset:9472
	ds_read_b64_tr_b16 v[152:153], v218 offset:11264
	ds_read_b64_tr_b16 v[154:155], v218 offset:12288
	ds_read_b64_tr_b16 v[158:159], v218 offset:12544
	ds_read_b64_tr_b16 v[156:157], v218 offset:11520
	ds_read_b64_tr_b16 v[160:161], v218 offset:13312
	ds_read_b64_tr_b16 v[162:163], v218 offset:14336
	ds_read_b64_tr_b16 v[166:167], v218 offset:14592
	ds_read_b64_tr_b16 v[164:165], v218 offset:13568
	ds_read_b64_tr_b16 v[168:169], v218 offset:15360
	ds_read_b64_tr_b16 v[170:171], v218 offset:16384
	ds_read_b64_tr_b16 v[174:175], v218 offset:16640
	ds_read_b64_tr_b16 v[172:173], v218 offset:15616
	s_waitcnt lgkmcnt(14)
	v_mfma_f32_32x32x16_bf16 v[48:63], v[32:35], v[64:67], 0
	s_add_i32 s15, s14, 1
	s_cmp_ge_u32 s15, s37
	v_mfma_f32_32x32x16_bf16 v[32:47], v[36:39], v[64:67], 0
	v_mfma_f32_32x32x16_bf16 v[48:63], v[96:99], v[68:71], v[48:63]
	v_mfma_f32_32x32x16_bf16 v[32:47], v[104:107], v[68:71], v[32:47]
	v_mfma_f32_32x32x16_bf16 v[48:63], v[114:117], v[72:75], v[48:63]
	v_mfma_f32_32x32x16_bf16 v[32:47], v[122:125], v[72:75], v[32:47]
	v_mfma_f32_32x32x16_bf16 v[48:63], v[118:121], v[76:79], v[48:63]
	v_mfma_f32_32x32x16_bf16 v[32:47], v[134:137], v[76:79], v[32:47]
	s_nop 10
	v_exp_f32_e32 v96, v48
	v_exp_f32_e32 v97, v49
	v_exp_f32_e32 v98, v50
	v_exp_f32_e32 v99, v51
	v_exp_f32_e32 v104, v52
	v_exp_f32_e32 v105, v53
	v_exp_f32_e32 v106, v54
	v_exp_f32_e32 v109, v32
	v_exp_f32_e32 v110, v33
	v_exp_f32_e32 v111, v34
	v_exp_f32_e32 v114, v35
	v_exp_f32_e32 v107, v55
	v_cvt_pk_bf16_f32 v32, v96, v97
	v_cvt_pk_bf16_f32 v33, v98, v99
	v_cvt_pk_bf16_f32 v34, v104, v105
	v_cvt_pk_bf16_f32 v35, v106, v107
	v_exp_f32_e32 v115, v36
	v_mfma_f32_32x32x16_bf16 v[0:15], v[138:141], v[32:35], v[0:15]
	v_exp_f32_e32 v116, v37
	v_exp_f32_e32 v117, v38
	v_exp_f32_e32 v118, v39
	v_exp_f32_e32 v119, v56
	v_exp_f32_e32 v120, v57
	v_exp_f32_e32 v126, v58
	v_exp_f32_e32 v125, v59
	s_waitcnt lgkmcnt(12)
	v_mfma_f32_32x32x16_bf16 v[16:31], v[146:149], v[32:35], v[16:31]
	v_exp_f32_e32 v124, v60
	v_exp_f32_e32 v123, v61
	v_exp_f32_e32 v122, v62
	v_exp_f32_e32 v121, v63
	v_cvt_pk_bf16_f32 v36, v109, v110
	v_cvt_pk_bf16_f32 v37, v111, v114
	v_cvt_pk_bf16_f32 v38, v115, v116
	v_cvt_pk_bf16_f32 v39, v117, v118
	v_cvt_pk_bf16_f32 v32, v119, v120
	v_cvt_pk_bf16_f32 v33, v126, v125
	v_cvt_pk_bf16_f32 v34, v124, v123
	v_cvt_pk_bf16_f32 v35, v122, v121
	v_exp_f32_e32 v138, v40
	s_waitcnt lgkmcnt(10)
	v_mfma_f32_32x32x16_bf16 v[0:15], v[152:155], v[32:35], v[0:15]
	v_exp_f32_e32 v137, v41
	v_exp_f32_e32 v136, v42
	v_exp_f32_e32 v134, v43
	v_exp_f32_e32 v131, v44
	v_exp_f32_e32 v135, v45
	v_exp_f32_e32 v133, v46
	v_exp_f32_e32 v127, v47
	s_waitcnt lgkmcnt(8)
	v_mfma_f32_32x32x16_bf16 v[16:31], v[156:159], v[32:35], v[16:31]
	v_cvt_pk_bf16_f32 v32, v138, v137
	v_cvt_pk_bf16_f32 v33, v136, v134
	v_cvt_pk_bf16_f32 v34, v131, v135
	v_cvt_pk_bf16_f32 v35, v133, v127
	s_waitcnt lgkmcnt(6)
	v_mfma_f32_32x32x16_bf16 v[0:15], v[160:163], v[36:39], v[0:15]
	s_waitcnt lgkmcnt(4)
	v_mfma_f32_32x32x16_bf16 v[16:31], v[164:167], v[36:39], v[16:31]
	s_waitcnt lgkmcnt(2)
	v_mfma_f32_32x32x16_bf16 v[0:15], v[168:171], v[32:35], v[0:15]
	s_waitcnt lgkmcnt(0)
	v_mfma_f32_32x32x16_bf16 v[16:31], v[172:175], v[32:35], v[16:31]
	s_cbranch_scc1 .LBB0_582
	s_cmp_ge_u32 s13, s37
	s_cbranch_scc1 .Lgqa_w0_tail
	s_waitcnt vmcnt(3)
	ds_write_b128 v193, v[88:91] offset:17408
	s_waitcnt vmcnt(2)
	ds_write_b128 v219, v[92:95] offset:26624
	s_branch .LBB0_582
.Lgqa_w0_tail:
	s_waitcnt vmcnt(1)
	ds_write_b128 v193, v[88:91] offset:17408
	s_waitcnt vmcnt(0)
	ds_write_b128 v219, v[92:95] offset:26624

.LBB0_584:
	ds_read_b128 v[32:35], v194 offset:17408
	ds_read_b128 v[140:143], v194 offset:17440
	ds_read_b128 v[36:39], v194 offset:22016
	ds_read_b128 v[146:149], v194 offset:22048
	ds_read_b128 v[152:155], v194 offset:17472
	ds_read_b128 v[156:159], v194 offset:17504
	ds_read_b128 v[160:163], v194 offset:22080
	ds_read_b128 v[164:167], v194 offset:22112
	ds_read_b64_tr_b16 v[168:169], v218 offset:26624
	ds_read_b64_tr_b16 v[170:171], v218 offset:27648
	ds_read_b64_tr_b16 v[174:175], v218 offset:27904
	ds_read_b64_tr_b16 v[172:173], v218 offset:26880
	ds_read_b64_tr_b16 v[176:177], v218 offset:28672
	ds_read_b64_tr_b16 v[178:179], v218 offset:29696
	ds_read_b64_tr_b16 v[182:183], v218 offset:29952
	ds_read_b64_tr_b16 v[180:181], v218 offset:28928
	ds_read_b64_tr_b16 v[184:185], v218 offset:30720
	ds_read_b64_tr_b16 v[186:187], v218 offset:31744
	ds_read_b64_tr_b16 v[190:191], v218 offset:32000
	ds_read_b64_tr_b16 v[188:189], v218 offset:30976
	ds_read_b64_tr_b16 v[196:197], v218 offset:32768
	ds_read_b64_tr_b16 v[198:199], v218 offset:33792
	ds_read_b64_tr_b16 v[202:203], v218 offset:34048
	ds_read_b64_tr_b16 v[200:201], v218 offset:33024
	s_waitcnt lgkmcnt(14)
	v_mfma_f32_32x32x16_bf16 v[48:63], v[32:35], v[64:67], 0
	s_andn2_b64 vcc, exec, s[10:11]
	v_mfma_f32_32x32x16_bf16 v[32:47], v[36:39], v[64:67], 0
	v_mfma_f32_32x32x16_bf16 v[48:63], v[140:143], v[68:71], v[48:63]
	v_mfma_f32_32x32x16_bf16 v[32:47], v[146:149], v[68:71], v[32:47]
	v_mfma_f32_32x32x16_bf16 v[48:63], v[152:155], v[72:75], v[48:63]
	v_mfma_f32_32x32x16_bf16 v[32:47], v[160:163], v[72:75], v[32:47]
	v_mfma_f32_32x32x16_bf16 v[48:63], v[156:159], v[76:79], v[48:63]
	v_mfma_f32_32x32x16_bf16 v[32:47], v[164:167], v[76:79], v[32:47]
	s_nop 10
	v_exp_f32_e32 v48, v48
	v_exp_f32_e32 v141, v58
	v_exp_f32_e32 v140, v59
	v_exp_f32_e32 v60, v60
	v_exp_f32_e32 v59, v61
	v_exp_f32_e32 v58, v62
	v_exp_f32_e32 v139, v32
	v_exp_f32_e32 v32, v49
	v_exp_f32_e32 v49, v33
	v_exp_f32_e32 v33, v50
	v_exp_f32_e32 v50, v34
	v_exp_f32_e32 v34, v51
	v_exp_f32_e32 v51, v35
	v_exp_f32_e32 v35, v52
	v_exp_f32_e32 v52, v36
	v_exp_f32_e32 v36, v53
	v_exp_f32_e32 v53, v37
	v_exp_f32_e32 v37, v54
	v_exp_f32_e32 v54, v38
	v_exp_f32_e32 v38, v55
	v_cvt_pk_bf16_f32 v146, v48, v32
	v_cvt_pk_bf16_f32 v147, v33, v34
	v_cvt_pk_bf16_f32 v148, v35, v36
	v_cvt_pk_bf16_f32 v149, v37, v38
	v_exp_f32_e32 v39, v39
	v_mfma_f32_32x32x16_bf16 v[0:15], v[168:171], v[146:149], v[0:15]
	v_exp_f32_e32 v55, v56
	v_exp_f32_e32 v56, v57
	v_exp_f32_e32 v57, v63
	v_cvt_pk_bf16_f32 v152, v139, v49
	v_cvt_pk_bf16_f32 v153, v50, v51
	v_cvt_pk_bf16_f32 v154, v52, v53
	v_cvt_pk_bf16_f32 v155, v54, v39
	s_waitcnt lgkmcnt(12)
	v_mfma_f32_32x32x16_bf16 v[16:31], v[172:175], v[146:149], v[16:31]
	v_cvt_pk_bf16_f32 v146, v55, v56
	v_cvt_pk_bf16_f32 v147, v141, v140
	v_cvt_pk_bf16_f32 v148, v60, v59
	v_cvt_pk_bf16_f32 v149, v58, v57
	v_exp_f32_e32 v63, v40
	v_exp_f32_e32 v62, v41
	v_exp_f32_e32 v61, v42
	s_waitcnt lgkmcnt(10)
	v_mfma_f32_32x32x16_bf16 v[0:15], v[176:179], v[146:149], v[0:15]
	v_exp_f32_e32 v43, v43
	v_exp_f32_e32 v41, v44
	v_exp_f32_e32 v44, v45
	v_exp_f32_e32 v42, v46
	v_exp_f32_e32 v40, v47
	s_waitcnt lgkmcnt(8)
	v_mfma_f32_32x32x16_bf16 v[16:31], v[180:183], v[146:149], v[16:31]
	v_cvt_pk_bf16_f32 v146, v63, v62
	v_cvt_pk_bf16_f32 v147, v61, v43
	v_cvt_pk_bf16_f32 v148, v41, v44
	v_cvt_pk_bf16_f32 v149, v42, v40
	s_waitcnt lgkmcnt(6)
	v_mfma_f32_32x32x16_bf16 v[0:15], v[184:187], v[152:155], v[0:15]
	s_waitcnt lgkmcnt(4)
	v_mfma_f32_32x32x16_bf16 v[16:31], v[188:191], v[152:155], v[16:31]
	s_waitcnt lgkmcnt(2)
	v_mfma_f32_32x32x16_bf16 v[0:15], v[196:199], v[146:149], v[0:15]
	s_waitcnt lgkmcnt(0)
	v_mfma_f32_32x32x16_bf16 v[16:31], v[200:203], v[146:149], v[16:31]
	s_cbranch_vccnz .LBB0_586
	s_cmp_ge_u32 s14, s12
	s_cbranch_scc1 .Lgqa_w1_tail
	s_waitcnt vmcnt(3)
	ds_write_b128 v193, v[80:83]
	s_waitcnt vmcnt(2)
	ds_write_b128 v219, v[84:87] offset:9216
	s_branch .LBB0_586
.Lgqa_w1_tail:
	s_waitcnt vmcnt(1)
	ds_write_b128 v193, v[80:83]
	s_waitcnt vmcnt(0)
	ds_write_b128 v219, v[84:87] offset:9216

; __device__ __forceinline__ float bflo(unsigned w) { return __uint_as_float(w << 16); }
; __device__ __forceinline__ float bfhi(unsigned w) { return __uint_as_float(w & 0xffff0000u); }
; __global__ void __launch_bounds__(512, 2) mega_fwd(Args a) {
;     ...
;                     {
;                         f32x16 X0, X1;
; #pragma unroll
;                         for (int r = 0; r < 16; ++r) { X0[r] = 0.f; X1[r] = 0.f; }
; #pragma unroll
;                         for (int s = 0; s < 2; ++s) {
;                             X0 = __builtin_amdgcn_mfma_f32_32x32x16_bf16(spf[0][s], qf[s], X0, 0, 0, 0);
;                             X1 = __builtin_amdgcn_mfma_f32_32x32x16_bf16(spf[1][s], qf[s], X1, 0, 0, 0);
;                         }
;                         const float dec = fexp2(lg2 * (float)(dir == 0 ? qi + 1 : 128 - qi));
; #pragma unroll
;                         for (int r = 0; r < 16; ++r) { O0[r] += dec * X0[r]; O1[r] += dec * X1[r]; }
;                     }
;                     float ss = 0.f;
; #pragma unroll
;                     for (int r = 0; r < 16; ++r) ss += O0[r] * O0[r] + O1[r] * O1[r];
;                     ss += shx(ss, 32, lane);
;                     const float rs = rsqrtf(ss * (1.f / 64.f) + EPS);
;                     const float* ng = IN(I_RNG) + ((size_t)(l * 2 + dir) * 4 + h) * 64;
;                     f32x4 yv[8];
; #pragma unroll
;                     for (int dt = 0; dt < 2; ++dt)
; #pragma unroll
;                         for (int rg = 0; rg < 4; ++rg) {
;                             const int d0 = 32 * dt + 8 * rg + 4 * hi;
;                             const u32x2 gt2 = gtv[dt * 4 + rg]; const f32x4 gn = *(const f32x4*)(ng + d0);
;                             const float g0 = bflo(gt2.x), g1 = bfhi(gt2.x), g2 = bflo(gt2.y), g3 = bfhi(gt2.y);
;                             f32x4 y;
;                             if (dt == 0) { y.x = O0[4 * rg]; y.y = O0[4 * rg + 1]; y.z = O0[4 * rg + 2]; y.w = O0[4 * rg + 3]; }
;                             else { y.x = O1[4 * rg]; y.y = O1[4 * rg + 1]; y.z = O1[4 * rg + 2]; y.w = O1[4 * rg + 3]; }
;                             y = y * rs * gn;
;                             y.x *= g0 * sigmoidf_(g0); y.y *= g1 * sigmoidf_(g1); y.z *= g2 * sigmoidf_(g2); y.w *= g3 * sigmoidf_(g3);
;                             yv[dt * 4 + rg] = y;
;                         }
.LBB0_612:
	s_waitcnt vmcnt(9)
	v_mfma_f32_32x32x16_bf16 v[16:31], v[84:87], v[68:71], 0
	s_load_dwordx2 s[20:21], s[88:89], 0xa0
	s_or_b32 s72, s19, s13
	s_mov_b32 s73, s79
	s_lshl_b64 s[72:73], s[72:73], 8
	s_waitcnt lgkmcnt(0)
	s_add_u32 s20, s20, s72
	s_addc_u32 s21, s21, s73
	v_mfma_f32_32x32x16_bf16 v[0:15], v[76:79], v[68:71], 0
	s_waitcnt vmcnt(8)
	v_mfma_f32_32x32x16_bf16 v[16:31], v[80:83], v[64:67], v[16:31]
	v_mfma_f32_32x32x16_bf16 v[0:15], v[72:75], v[64:67], v[0:15]
	v_mul_f32_e32 v64, v103, v122
	v_exp_f32_e32 v64, v64
	s_nop 8
	v_pk_fma_f32 v[16:17], v[64:65], v[16:17], v[32:33] op_sel_hi:[0,1,1]
	v_pk_fma_f32 v[18:19], v[64:65], v[18:19], v[34:35] op_sel_hi:[0,1,1]
	v_pk_fma_f32 v[0:1], v[64:65], v[0:1], v[48:49] op_sel_hi:[0,1,1]
	v_pk_mul_f32 v[32:33], v[16:17], v[16:17]
	v_pk_fma_f32 v[2:3], v[64:65], v[2:3], v[50:51] op_sel_hi:[0,1,1]
	v_pk_fma_f32 v[32:33], v[0:1], v[0:1], v[32:33]
	v_pk_mul_f32 v[34:35], v[18:19], v[18:19]
	v_pk_fma_f32 v[20:21], v[64:65], v[20:21], v[36:37] op_sel_hi:[0,1,1]
	v_pk_fma_f32 v[34:35], v[2:3], v[2:3], v[34:35]
	v_add_f32_e32 v32, v32, v33
	v_pk_fma_f32 v[4:5], v[64:65], v[4:5], v[52:53] op_sel_hi:[0,1,1]
	v_pk_mul_f32 v[36:37], v[20:21], v[20:21]
	v_add_f32_e32 v32, v32, v34
	v_pk_fma_f32 v[22:23], v[64:65], v[22:23], v[38:39] op_sel_hi:[0,1,1]
	v_pk_fma_f32 v[36:37], v[4:5], v[4:5], v[36:37]
	v_add_f32_e32 v32, v32, v35
	v_pk_fma_f32 v[6:7], v[64:65], v[6:7], v[54:55] op_sel_hi:[0,1,1]
	v_pk_mul_f32 v[38:39], v[22:23], v[22:23]
	v_add_f32_e32 v32, v32, v36
	v_pk_fma_f32 v[38:39], v[6:7], v[6:7], v[38:39]
	v_add_f32_e32 v32, v32, v37
	v_add_f32_e32 v32, v32, v38
	v_lshl_add_u64 v[34:35], v[96:97], 2, s[20:21]
	v_add_f32_e32 v32, v32, v39
	global_load_dwordx4 v[36:39], v[34:35], off
	global_load_dwordx4 v[216:219], v[34:35], off offset:32
	global_load_dwordx4 v[220:223], v[34:35], off offset:64
	global_load_dwordx4 v[224:227], v[34:35], off offset:96
	global_load_dwordx4 v[228:231], v[34:35], off offset:128
	global_load_dwordx4 v[232:235], v[34:35], off offset:160
	global_load_dwordx4 v[236:239], v[34:35], off offset:192
	global_load_dwordx4 v[240:243], v[34:35], off offset:224
	v_pk_fma_f32 v[24:25], v[64:65], v[24:25], v[40:41] op_sel_hi:[0,1,1]
	v_pk_fma_f32 v[8:9], v[64:65], v[8:9], v[56:57] op_sel_hi:[0,1,1]
	v_pk_mul_f32 v[40:41], v[24:25], v[24:25]
	v_pk_fma_f32 v[26:27], v[64:65], v[26:27], v[42:43] op_sel_hi:[0,1,1]
	v_pk_fma_f32 v[40:41], v[8:9], v[8:9], v[40:41]
	v_pk_fma_f32 v[10:11], v[64:65], v[10:11], v[58:59] op_sel_hi:[0,1,1]
	v_pk_mul_f32 v[42:43], v[26:27], v[26:27]
	v_add_f32_e32 v32, v32, v40
	v_pk_fma_f32 v[28:29], v[64:65], v[28:29], v[44:45] op_sel_hi:[0,1,1]
	v_pk_fma_f32 v[42:43], v[10:11], v[10:11], v[42:43]
	v_add_f32_e32 v32, v32, v41
	v_pk_fma_f32 v[12:13], v[64:65], v[12:13], v[60:61] op_sel_hi:[0,1,1]
	v_pk_mul_f32 v[44:45], v[28:29], v[28:29]
	v_add_f32_e32 v32, v32, v42
	v_pk_fma_f32 v[30:31], v[64:65], v[30:31], v[46:47] op_sel_hi:[0,1,1]
	v_pk_fma_f32 v[44:45], v[12:13], v[12:13], v[44:45]
	v_add_f32_e32 v32, v32, v43
	v_pk_fma_f32 v[14:15], v[64:65], v[14:15], v[62:63] op_sel_hi:[0,1,1]
	v_pk_mul_f32 v[46:47], v[30:31], v[30:31]
	v_add_f32_e32 v32, v32, v44
	v_pk_fma_f32 v[46:47], v[14:15], v[14:15], v[46:47]
	v_add_f32_e32 v32, v32, v45
	v_add_f32_e32 v32, v32, v46
	v_add_f32_e32 v32, v32, v47
	ds_bpermute_b32 v33, v123, v32
	s_waitcnt vmcnt(8)
	v_lshlrev_b32_e32 v40, 16, v119
	v_and_b32_e32 v41, 0xffff0000, v119
	s_waitcnt lgkmcnt(0)
	v_add_f32_e32 v32, v32, v33
	v_fmamk_f32 v32, v32, 0x3c800000, v205
	v_cmp_gt_f32_e32 vcc, s2, v32
	v_mul_f32_e32 v33, 0x4b800000, v32
	s_nop 0
	v_cndmask_b32_e32 v32, v32, v33, vcc
	v_rsq_f32_e32 v32, v32
	s_nop 0
	v_mul_f32_e32 v33, 0x45800000, v32
	v_cndmask_b32_e32 v32, v32, v33, vcc
	v_pk_mul_f32 v[0:1], v[32:33], v[0:1] op_sel_hi:[0,1]
	v_pk_mul_f32 v[2:3], v[32:33], v[2:3] op_sel_hi:[0,1]
	s_waitcnt vmcnt(0)
	v_pk_mul_f32 v[0:1], v[36:37], v[0:1]
	v_lshlrev_b32_e32 v36, 16, v118
	v_and_b32_e32 v37, 0xffff0000, v118
	v_mul_f32_e32 v33, 0xbfb8aa3b, v36
	v_pk_mul_f32 v[2:3], v[38:39], v[2:3]
	v_exp_f32_e32 v38, v33
	v_mul_f32_e32 v33, 0xbfb8aa3b, v37
	v_exp_f32_e32 v39, v33
	v_mul_f32_e32 v33, 0xbfb8aa3b, v40
	v_exp_f32_e32 v42, v33
	v_mul_f32_e32 v33, 0xbfb8aa3b, v41
	v_exp_f32_e32 v43, v33
	v_pk_add_f32 v[38:39], v[38:39], 1.0 op_sel_hi:[1,0]
	v_pk_add_f32 v[42:43], v[42:43], 1.0 op_sel_hi:[1,0]
	s_nop 0
	v_div_scale_f32 v33, s[20:21], v43, v43, 1.0
	v_rcp_f32_e32 v44, v33
	s_nop 0
	v_fma_f32 v45, -v33, v44, 1.0
	v_fmac_f32_e32 v44, v45, v44
	v_div_scale_f32 v45, vcc, 1.0, v43, 1.0
	v_mul_f32_e32 v46, v45, v44
	v_fma_f32 v47, -v33, v46, v45
	v_fmac_f32_e32 v46, v47, v44
	v_fma_f32 v33, -v33, v46, v45
	v_div_fmas_f32 v33, v33, v44, v46
	v_div_fixup_f32 v43, v33, v43, 1.0
	v_div_scale_f32 v33, s[20:21], v42, v42, 1.0
	v_rcp_f32_e32 v44, v33
	s_nop 0
	v_fma_f32 v45, -v33, v44, 1.0
	v_fmac_f32_e32 v44, v45, v44
	v_div_scale_f32 v45, vcc, 1.0, v42, 1.0
	v_mul_f32_e32 v46, v45, v44
	v_fma_f32 v47, -v33, v46, v45
	v_fmac_f32_e32 v46, v47, v44
	v_fma_f32 v33, -v33, v46, v45
	v_div_fmas_f32 v33, v33, v44, v46
	v_div_fixup_f32 v42, v33, v42, 1.0
	v_div_scale_f32 v33, s[20:21], v39, v39, 1.0
	v_rcp_f32_e32 v44, v33
	s_nop 0
	v_fma_f32 v45, -v33, v44, 1.0
	v_fmac_f32_e32 v44, v45, v44
	v_div_scale_f32 v45, vcc, 1.0, v39, 1.0
	v_mul_f32_e32 v46, v45, v44
	v_fma_f32 v47, -v33, v46, v45
	v_fmac_f32_e32 v46, v47, v44
	v_fma_f32 v33, -v33, v46, v45
	v_div_fmas_f32 v33, v33, v44, v46
	v_div_fixup_f32 v39, v33, v39, 1.0
	v_div_scale_f32 v33, s[20:21], v38, v38, 1.0
	v_rcp_f32_e32 v44, v33
	s_nop 0
	v_fma_f32 v45, -v33, v44, 1.0
	v_fmac_f32_e32 v44, v45, v44
	v_div_scale_f32 v45, vcc, 1.0, v38, 1.0
	v_mul_f32_e32 v46, v45, v44
	v_fma_f32 v47, -v33, v46, v45
	v_fmac_f32_e32 v46, v47, v44
	v_fma_f32 v33, -v33, v46, v45
	v_div_fmas_f32 v33, v33, v44, v46
	v_div_fixup_f32 v38, v33, v38, 1.0
	v_pk_mul_f32 v[36:37], v[38:39], v[36:37]
	v_pk_mul_f32 v[38:39], v[42:43], v[40:41]
	v_pk_mul_f32 v[0:1], v[36:37], v[0:1]
	v_pk_mul_f32 v[2:3], v[38:39], v[2:3]
	v_mov_b32_e32 v36, v216
	v_mov_b32_e32 v37, v217
	v_mov_b32_e32 v38, v218
	v_mov_b32_e32 v39, v219
	v_pk_mul_f32 v[4:5], v[32:33], v[4:5] op_sel_hi:[0,1]
	v_pk_mul_f32 v[6:7], v[32:33], v[6:7] op_sel_hi:[0,1]
	v_lshlrev_b32_e32 v40, 16, v117
	v_and_b32_e32 v41, 0xffff0000, v117
	s_waitcnt vmcnt(0)
; __device__ __forceinline__ float bflo(unsigned w) { return __uint_as_float(w << 16); }
; __device__ __forceinline__ float bfhi(unsigned w) { return __uint_as_float(w & 0xffff0000u); }
; __device__ __forceinline__ float sigmoidf_(float x) { return 1.0f / (1.0f + __expf(-x)); }
; __global__ void __launch_bounds__(512, 2) mega_fwd(Args a) {
;     ...
;                     const float* ng = IN(I_RNG) + ((size_t)(l * 2 + dir) * 4 + h) * 64;
;                     f32x4 yv[8];
; #pragma unroll
;                     for (int dt = 0; dt < 2; ++dt)
; #pragma unroll
;                         for (int rg = 0; rg < 4; ++rg) {
;                             const int d0 = 32 * dt + 8 * rg + 4 * hi;
;                             const u32x2 gt2 = gtv[dt * 4 + rg]; const f32x4 gn = *(const f32x4*)(ng + d0);
;                             const float g0 = bflo(gt2.x), g1 = bfhi(gt2.x), g2 = bflo(gt2.y), g3 = bfhi(gt2.y);
;                             f32x4 y;
;                             if (dt == 0) { y.x = O0[4 * rg]; y.y = O0[4 * rg + 1]; y.z = O0[4 * rg + 2]; y.w = O0[4 * rg + 3]; }
;                             else { y.x = O1[4 * rg]; y.y = O1[4 * rg + 1]; y.z = O1[4 * rg + 2]; y.w = O1[4 * rg + 3]; }
;                             y = y * rs * gn;
;                             y.x *= g0 * sigmoidf_(g0); y.y *= g1 * sigmoidf_(g1); y.z *= g2 * sigmoidf_(g2); y.w *= g3 * sigmoidf_(g3);
;                             yv[dt * 4 + rg] = y;
;                         }
	v_pk_mul_f32 v[4:5], v[36:37], v[4:5]
	v_lshlrev_b32_e32 v36, 16, v116
	v_and_b32_e32 v37, 0xffff0000, v116
	v_mul_f32_e32 v33, 0xbfb8aa3b, v36
	v_pk_mul_f32 v[6:7], v[38:39], v[6:7]
	v_exp_f32_e32 v38, v33
	v_mul_f32_e32 v33, 0xbfb8aa3b, v37
	v_exp_f32_e32 v39, v33
	v_mul_f32_e32 v33, 0xbfb8aa3b, v40
	v_exp_f32_e32 v42, v33
	v_mul_f32_e32 v33, 0xbfb8aa3b, v41
	v_exp_f32_e32 v43, v33
	v_pk_add_f32 v[38:39], v[38:39], 1.0 op_sel_hi:[1,0]
	v_pk_add_f32 v[42:43], v[42:43], 1.0 op_sel_hi:[1,0]
	s_nop 0
	v_div_scale_f32 v33, s[20:21], v43, v43, 1.0
	v_rcp_f32_e32 v44, v33
	s_nop 0
	v_fma_f32 v45, -v33, v44, 1.0
	v_fmac_f32_e32 v44, v45, v44
	v_div_scale_f32 v45, vcc, 1.0, v43, 1.0
	v_mul_f32_e32 v46, v45, v44
	v_fma_f32 v47, -v33, v46, v45
	v_fmac_f32_e32 v46, v47, v44
	v_fma_f32 v33, -v33, v46, v45
	v_div_fmas_f32 v33, v33, v44, v46
	v_div_fixup_f32 v43, v33, v43, 1.0
	v_div_scale_f32 v33, s[20:21], v42, v42, 1.0
	v_rcp_f32_e32 v44, v33
	s_nop 0
	v_fma_f32 v45, -v33, v44, 1.0
	v_fmac_f32_e32 v44, v45, v44
	v_div_scale_f32 v45, vcc, 1.0, v42, 1.0
	v_mul_f32_e32 v46, v45, v44
	v_fma_f32 v47, -v33, v46, v45
	v_fmac_f32_e32 v46, v47, v44
	v_fma_f32 v33, -v33, v46, v45
	v_div_fmas_f32 v33, v33, v44, v46
	v_div_fixup_f32 v42, v33, v42, 1.0
	v_div_scale_f32 v33, s[20:21], v39, v39, 1.0
	v_rcp_f32_e32 v44, v33
	s_nop 0
	v_fma_f32 v45, -v33, v44, 1.0
	v_fmac_f32_e32 v44, v45, v44
	v_div_scale_f32 v45, vcc, 1.0, v39, 1.0
	v_mul_f32_e32 v46, v45, v44
	v_fma_f32 v47, -v33, v46, v45
	v_fmac_f32_e32 v46, v47, v44
	v_fma_f32 v33, -v33, v46, v45
	v_div_fmas_f32 v33, v33, v44, v46
	v_div_fixup_f32 v39, v33, v39, 1.0
	v_div_scale_f32 v33, s[20:21], v38, v38, 1.0
	v_rcp_f32_e32 v44, v33
	s_nop 0
	v_fma_f32 v45, -v33, v44, 1.0
	v_fmac_f32_e32 v44, v45, v44
	v_div_scale_f32 v45, vcc, 1.0, v38, 1.0
	v_mul_f32_e32 v46, v45, v44
	v_fma_f32 v47, -v33, v46, v45
	v_fmac_f32_e32 v46, v47, v44
	v_fma_f32 v33, -v33, v46, v45
	v_div_fmas_f32 v33, v33, v44, v46
	v_div_fixup_f32 v38, v33, v38, 1.0
	v_pk_mul_f32 v[36:37], v[38:39], v[36:37]
	v_pk_mul_f32 v[38:39], v[42:43], v[40:41]
	v_pk_mul_f32 v[4:5], v[36:37], v[4:5]
	v_pk_mul_f32 v[6:7], v[38:39], v[6:7]
	v_mov_b32_e32 v36, v220
	v_mov_b32_e32 v37, v221
	v_mov_b32_e32 v38, v222
	v_mov_b32_e32 v39, v223
	v_pk_mul_f32 v[8:9], v[32:33], v[8:9] op_sel_hi:[0,1]
	v_pk_mul_f32 v[10:11], v[32:33], v[10:11] op_sel_hi:[0,1]
	v_lshlrev_b32_e32 v40, 16, v115
	v_and_b32_e32 v41, 0xffff0000, v115
	s_waitcnt vmcnt(0)
	v_pk_mul_f32 v[8:9], v[36:37], v[8:9]
	v_lshlrev_b32_e32 v36, 16, v114
	v_and_b32_e32 v37, 0xffff0000, v114
	v_mul_f32_e32 v33, 0xbfb8aa3b, v36
	v_pk_mul_f32 v[10:11], v[38:39], v[10:11]
	v_exp_f32_e32 v38, v33
	v_mul_f32_e32 v33, 0xbfb8aa3b, v37
	v_exp_f32_e32 v39, v33
	v_mul_f32_e32 v33, 0xbfb8aa3b, v40
	v_exp_f32_e32 v42, v33
	v_mul_f32_e32 v33, 0xbfb8aa3b, v41
	v_exp_f32_e32 v43, v33
	v_pk_add_f32 v[38:39], v[38:39], 1.0 op_sel_hi:[1,0]
	v_pk_add_f32 v[42:43], v[42:43], 1.0 op_sel_hi:[1,0]
	s_nop 0
	v_div_scale_f32 v33, s[20:21], v43, v43, 1.0
	v_rcp_f32_e32 v44, v33
	s_nop 0
	v_fma_f32 v45, -v33, v44, 1.0
	v_fmac_f32_e32 v44, v45, v44
	v_div_scale_f32 v45, vcc, 1.0, v43, 1.0
	v_mul_f32_e32 v46, v45, v44
	v_fma_f32 v47, -v33, v46, v45
	v_fmac_f32_e32 v46, v47, v44
	v_fma_f32 v33, -v33, v46, v45
	v_div_fmas_f32 v33, v33, v44, v46
	v_div_fixup_f32 v43, v33, v43, 1.0
	v_div_scale_f32 v33, s[20:21], v42, v42, 1.0
	v_rcp_f32_e32 v44, v33
	s_nop 0
	v_fma_f32 v45, -v33, v44, 1.0
	v_fmac_f32_e32 v44, v45, v44
	v_div_scale_f32 v45, vcc, 1.0, v42, 1.0
	v_mul_f32_e32 v46, v45, v44
	v_fma_f32 v47, -v33, v46, v45
	v_fmac_f32_e32 v46, v47, v44
	v_fma_f32 v33, -v33, v46, v45
	v_div_fmas_f32 v33, v33, v44, v46
	v_div_fixup_f32 v42, v33, v42, 1.0
	v_div_scale_f32 v33, s[20:21], v39, v39, 1.0
	v_rcp_f32_e32 v44, v33
	s_nop 0
	v_fma_f32 v45, -v33, v44, 1.0
	v_fmac_f32_e32 v44, v45, v44
	v_div_scale_f32 v45, vcc, 1.0, v39, 1.0
	v_mul_f32_e32 v46, v45, v44
	v_fma_f32 v47, -v33, v46, v45
	v_fmac_f32_e32 v46, v47, v44
	v_fma_f32 v33, -v33, v46, v45
	v_div_fmas_f32 v33, v33, v44, v46
	v_div_fixup_f32 v39, v33, v39, 1.0
	v_div_scale_f32 v33, s[20:21], v38, v38, 1.0
	v_rcp_f32_e32 v44, v33
	s_nop 0
	v_fma_f32 v45, -v33, v44, 1.0
	v_fmac_f32_e32 v44, v45, v44
	v_div_scale_f32 v45, vcc, 1.0, v38, 1.0
	v_mul_f32_e32 v46, v45, v44
	v_fma_f32 v47, -v33, v46, v45
	v_fmac_f32_e32 v46, v47, v44
	v_fma_f32 v33, -v33, v46, v45
	v_div_fmas_f32 v33, v33, v44, v46
	v_div_fixup_f32 v38, v33, v38, 1.0
	v_pk_mul_f32 v[36:37], v[38:39], v[36:37]
	v_pk_mul_f32 v[38:39], v[42:43], v[40:41]
	v_pk_mul_f32 v[8:9], v[36:37], v[8:9]
	v_pk_mul_f32 v[10:11], v[38:39], v[10:11]
	v_mov_b32_e32 v36, v224
	v_mov_b32_e32 v37, v225
	v_mov_b32_e32 v38, v226
	v_mov_b32_e32 v39, v227
	v_pk_mul_f32 v[12:13], v[32:33], v[12:13] op_sel_hi:[0,1]
	v_pk_mul_f32 v[14:15], v[32:33], v[14:15] op_sel_hi:[0,1]
	v_lshlrev_b32_e32 v40, 16, v113
	v_and_b32_e32 v41, 0xffff0000, v113
	s_waitcnt vmcnt(0)
; __device__ __forceinline__ float bflo(unsigned w) { return __uint_as_float(w << 16); }
; __device__ __forceinline__ float bfhi(unsigned w) { return __uint_as_float(w & 0xffff0000u); }
; __device__ __forceinline__ float sigmoidf_(float x) { return 1.0f / (1.0f + __expf(-x)); }
; __global__ void __launch_bounds__(512, 2) mega_fwd(Args a) {
;     ...
;                     const float* ng = IN(I_RNG) + ((size_t)(l * 2 + dir) * 4 + h) * 64;
;                     f32x4 yv[8];
; #pragma unroll
;                     for (int dt = 0; dt < 2; ++dt)
; #pragma unroll
;                         for (int rg = 0; rg < 4; ++rg) {
;                             const int d0 = 32 * dt + 8 * rg + 4 * hi;
;                             const u32x2 gt2 = gtv[dt * 4 + rg]; const f32x4 gn = *(const f32x4*)(ng + d0);
;                             const float g0 = bflo(gt2.x), g1 = bfhi(gt2.x), g2 = bflo(gt2.y), g3 = bfhi(gt2.y);
;                             f32x4 y;
;                             if (dt == 0) { y.x = O0[4 * rg]; y.y = O0[4 * rg + 1]; y.z = O0[4 * rg + 2]; y.w = O0[4 * rg + 3]; }
;                             else { y.x = O1[4 * rg]; y.y = O1[4 * rg + 1]; y.z = O1[4 * rg + 2]; y.w = O1[4 * rg + 3]; }
;                             y = y * rs * gn;
;                             y.x *= g0 * sigmoidf_(g0); y.y *= g1 * sigmoidf_(g1); y.z *= g2 * sigmoidf_(g2); y.w *= g3 * sigmoidf_(g3);
;                             yv[dt * 4 + rg] = y;
;                         }
	v_pk_mul_f32 v[12:13], v[36:37], v[12:13]
	v_lshlrev_b32_e32 v36, 16, v112
	v_and_b32_e32 v37, 0xffff0000, v112
	v_mul_f32_e32 v33, 0xbfb8aa3b, v36
	v_pk_mul_f32 v[14:15], v[38:39], v[14:15]
	v_exp_f32_e32 v38, v33
	v_mul_f32_e32 v33, 0xbfb8aa3b, v37
	v_exp_f32_e32 v39, v33
	v_mul_f32_e32 v33, 0xbfb8aa3b, v40
	v_exp_f32_e32 v42, v33
	v_mul_f32_e32 v33, 0xbfb8aa3b, v41
	v_exp_f32_e32 v43, v33
	v_pk_add_f32 v[38:39], v[38:39], 1.0 op_sel_hi:[1,0]
	v_pk_add_f32 v[42:43], v[42:43], 1.0 op_sel_hi:[1,0]
	s_nop 0
	v_div_scale_f32 v33, s[20:21], v43, v43, 1.0
	v_rcp_f32_e32 v44, v33
	s_nop 0
	v_fma_f32 v45, -v33, v44, 1.0
	v_fmac_f32_e32 v44, v45, v44
	v_div_scale_f32 v45, vcc, 1.0, v43, 1.0
	v_mul_f32_e32 v46, v45, v44
	v_fma_f32 v47, -v33, v46, v45
	v_fmac_f32_e32 v46, v47, v44
	v_fma_f32 v33, -v33, v46, v45
	v_div_fmas_f32 v33, v33, v44, v46
	v_div_fixup_f32 v43, v33, v43, 1.0
	v_div_scale_f32 v33, s[20:21], v42, v42, 1.0
	v_rcp_f32_e32 v44, v33
	s_nop 0
	v_fma_f32 v45, -v33, v44, 1.0
	v_fmac_f32_e32 v44, v45, v44
	v_div_scale_f32 v45, vcc, 1.0, v42, 1.0
	v_mul_f32_e32 v46, v45, v44
	v_fma_f32 v47, -v33, v46, v45
	v_fmac_f32_e32 v46, v47, v44
	v_fma_f32 v33, -v33, v46, v45
	v_div_fmas_f32 v33, v33, v44, v46
	v_div_fixup_f32 v42, v33, v42, 1.0
	v_div_scale_f32 v33, s[20:21], v39, v39, 1.0
	v_rcp_f32_e32 v44, v33
	s_nop 0
	v_fma_f32 v45, -v33, v44, 1.0
	v_fmac_f32_e32 v44, v45, v44
	v_div_scale_f32 v45, vcc, 1.0, v39, 1.0
	v_mul_f32_e32 v46, v45, v44
	v_fma_f32 v47, -v33, v46, v45
	v_fmac_f32_e32 v46, v47, v44
	v_fma_f32 v33, -v33, v46, v45
	v_div_fmas_f32 v33, v33, v44, v46
	v_div_fixup_f32 v39, v33, v39, 1.0
	v_div_scale_f32 v33, s[20:21], v38, v38, 1.0
	v_rcp_f32_e32 v44, v33
	s_nop 0
	v_fma_f32 v45, -v33, v44, 1.0
	v_fmac_f32_e32 v44, v45, v44
	v_div_scale_f32 v45, vcc, 1.0, v38, 1.0
	v_mul_f32_e32 v46, v45, v44
	v_fma_f32 v47, -v33, v46, v45
	v_fmac_f32_e32 v46, v47, v44
	v_fma_f32 v33, -v33, v46, v45
	v_div_fmas_f32 v33, v33, v44, v46
	v_div_fixup_f32 v38, v33, v38, 1.0
	v_pk_mul_f32 v[36:37], v[38:39], v[36:37]
	v_pk_mul_f32 v[38:39], v[42:43], v[40:41]
	v_pk_mul_f32 v[12:13], v[36:37], v[12:13]
	v_pk_mul_f32 v[14:15], v[38:39], v[14:15]
	v_mov_b32_e32 v36, v228
	v_mov_b32_e32 v37, v229
	v_mov_b32_e32 v38, v230
	v_mov_b32_e32 v39, v231
	v_pk_mul_f32 v[16:17], v[32:33], v[16:17] op_sel_hi:[0,1]
	v_pk_mul_f32 v[18:19], v[32:33], v[18:19] op_sel_hi:[0,1]
	v_lshlrev_b32_e32 v40, 16, v111
	v_and_b32_e32 v41, 0xffff0000, v111
	s_waitcnt vmcnt(0)
	v_pk_mul_f32 v[16:17], v[36:37], v[16:17]
	v_lshlrev_b32_e32 v36, 16, v110
	v_and_b32_e32 v37, 0xffff0000, v110
	v_mul_f32_e32 v33, 0xbfb8aa3b, v36
	v_pk_mul_f32 v[18:19], v[38:39], v[18:19]
	v_exp_f32_e32 v38, v33
	v_mul_f32_e32 v33, 0xbfb8aa3b, v37
	v_exp_f32_e32 v39, v33
	v_mul_f32_e32 v33, 0xbfb8aa3b, v40
	v_exp_f32_e32 v42, v33
	v_mul_f32_e32 v33, 0xbfb8aa3b, v41
	v_exp_f32_e32 v43, v33
	v_pk_add_f32 v[38:39], v[38:39], 1.0 op_sel_hi:[1,0]
	v_pk_add_f32 v[42:43], v[42:43], 1.0 op_sel_hi:[1,0]
	s_nop 0
	v_div_scale_f32 v33, s[20:21], v43, v43, 1.0
	v_rcp_f32_e32 v44, v33
	s_nop 0
	v_fma_f32 v45, -v33, v44, 1.0
	v_fmac_f32_e32 v44, v45, v44
	v_div_scale_f32 v45, vcc, 1.0, v43, 1.0
	v_mul_f32_e32 v46, v45, v44
	v_fma_f32 v47, -v33, v46, v45
	v_fmac_f32_e32 v46, v47, v44
	v_fma_f32 v33, -v33, v46, v45
	v_div_fmas_f32 v33, v33, v44, v46
	v_div_fixup_f32 v43, v33, v43, 1.0
	v_div_scale_f32 v33, s[20:21], v42, v42, 1.0
	v_rcp_f32_e32 v44, v33
	s_nop 0
	v_fma_f32 v45, -v33, v44, 1.0
	v_fmac_f32_e32 v44, v45, v44
	v_div_scale_f32 v45, vcc, 1.0, v42, 1.0
	v_mul_f32_e32 v46, v45, v44
	v_fma_f32 v47, -v33, v46, v45
	v_fmac_f32_e32 v46, v47, v44
	v_fma_f32 v33, -v33, v46, v45
	v_div_fmas_f32 v33, v33, v44, v46
	v_div_fixup_f32 v42, v33, v42, 1.0
	v_div_scale_f32 v33, s[20:21], v39, v39, 1.0
	v_rcp_f32_e32 v44, v33
	s_nop 0
	v_fma_f32 v45, -v33, v44, 1.0
	v_fmac_f32_e32 v44, v45, v44
	v_div_scale_f32 v45, vcc, 1.0, v39, 1.0
	v_mul_f32_e32 v46, v45, v44
	v_fma_f32 v47, -v33, v46, v45
	v_fmac_f32_e32 v46, v47, v44
	v_fma_f32 v33, -v33, v46, v45
	v_div_fmas_f32 v33, v33, v44, v46
	v_div_fixup_f32 v39, v33, v39, 1.0
	v_div_scale_f32 v33, s[20:21], v38, v38, 1.0
	v_rcp_f32_e32 v44, v33
	s_nop 0
	v_fma_f32 v45, -v33, v44, 1.0
	v_fmac_f32_e32 v44, v45, v44
	v_div_scale_f32 v45, vcc, 1.0, v38, 1.0
	v_mul_f32_e32 v46, v45, v44
	v_fma_f32 v47, -v33, v46, v45
	v_fmac_f32_e32 v46, v47, v44
	v_fma_f32 v33, -v33, v46, v45
	v_div_fmas_f32 v33, v33, v44, v46
	v_div_fixup_f32 v38, v33, v38, 1.0
	v_pk_mul_f32 v[36:37], v[38:39], v[36:37]
	v_pk_mul_f32 v[38:39], v[42:43], v[40:41]
	v_pk_mul_f32 v[16:17], v[36:37], v[16:17]
	v_pk_mul_f32 v[18:19], v[38:39], v[18:19]
	v_mov_b32_e32 v36, v232
	v_mov_b32_e32 v37, v233
	v_mov_b32_e32 v38, v234
	v_mov_b32_e32 v39, v235
	v_pk_mul_f32 v[20:21], v[32:33], v[20:21] op_sel_hi:[0,1]
	v_pk_mul_f32 v[22:23], v[32:33], v[22:23] op_sel_hi:[0,1]
	v_lshlrev_b32_e32 v40, 16, v109
	v_and_b32_e32 v41, 0xffff0000, v109
	s_waitcnt vmcnt(0)
; __device__ __forceinline__ float bflo(unsigned w) { return __uint_as_float(w << 16); }
; __device__ __forceinline__ float bfhi(unsigned w) { return __uint_as_float(w & 0xffff0000u); }
; __device__ __forceinline__ float sigmoidf_(float x) { return 1.0f / (1.0f + __expf(-x)); }
; __global__ void __launch_bounds__(512, 2) mega_fwd(Args a) {
;     ...
;                     const float* ng = IN(I_RNG) + ((size_t)(l * 2 + dir) * 4 + h) * 64;
;                     f32x4 yv[8];
; #pragma unroll
;                     for (int dt = 0; dt < 2; ++dt)
; #pragma unroll
;                         for (int rg = 0; rg < 4; ++rg) {
;                             const int d0 = 32 * dt + 8 * rg + 4 * hi;
;                             const u32x2 gt2 = gtv[dt * 4 + rg]; const f32x4 gn = *(const f32x4*)(ng + d0);
;                             const float g0 = bflo(gt2.x), g1 = bfhi(gt2.x), g2 = bflo(gt2.y), g3 = bfhi(gt2.y);
;                             f32x4 y;
;                             if (dt == 0) { y.x = O0[4 * rg]; y.y = O0[4 * rg + 1]; y.z = O0[4 * rg + 2]; y.w = O0[4 * rg + 3]; }
;                             else { y.x = O1[4 * rg]; y.y = O1[4 * rg + 1]; y.z = O1[4 * rg + 2]; y.w = O1[4 * rg + 3]; }
;                             y = y * rs * gn;
;                             y.x *= g0 * sigmoidf_(g0); y.y *= g1 * sigmoidf_(g1); y.z *= g2 * sigmoidf_(g2); y.w *= g3 * sigmoidf_(g3);
;                             yv[dt * 4 + rg] = y;
;                         }
	v_pk_mul_f32 v[20:21], v[36:37], v[20:21]
	v_lshlrev_b32_e32 v36, 16, v108
	v_and_b32_e32 v37, 0xffff0000, v108
	v_mul_f32_e32 v33, 0xbfb8aa3b, v36
	v_pk_mul_f32 v[22:23], v[38:39], v[22:23]
	v_exp_f32_e32 v38, v33
	v_mul_f32_e32 v33, 0xbfb8aa3b, v37
	v_exp_f32_e32 v39, v33
	v_mul_f32_e32 v33, 0xbfb8aa3b, v40
	v_exp_f32_e32 v42, v33
	v_mul_f32_e32 v33, 0xbfb8aa3b, v41
	v_exp_f32_e32 v43, v33
	v_pk_add_f32 v[38:39], v[38:39], 1.0 op_sel_hi:[1,0]
	v_pk_add_f32 v[42:43], v[42:43], 1.0 op_sel_hi:[1,0]
	s_nop 0
	v_div_scale_f32 v33, s[20:21], v43, v43, 1.0
	v_rcp_f32_e32 v44, v33
	s_nop 0
	v_fma_f32 v45, -v33, v44, 1.0
	v_fmac_f32_e32 v44, v45, v44
	v_div_scale_f32 v45, vcc, 1.0, v43, 1.0
	v_mul_f32_e32 v46, v45, v44
	v_fma_f32 v47, -v33, v46, v45
	v_fmac_f32_e32 v46, v47, v44
	v_fma_f32 v33, -v33, v46, v45
	v_div_fmas_f32 v33, v33, v44, v46
	v_div_fixup_f32 v43, v33, v43, 1.0
	v_div_scale_f32 v33, s[20:21], v42, v42, 1.0
	v_rcp_f32_e32 v44, v33
	s_nop 0
	v_fma_f32 v45, -v33, v44, 1.0
	v_fmac_f32_e32 v44, v45, v44
	v_div_scale_f32 v45, vcc, 1.0, v42, 1.0
	v_mul_f32_e32 v46, v45, v44
	v_fma_f32 v47, -v33, v46, v45
	v_fmac_f32_e32 v46, v47, v44
	v_fma_f32 v33, -v33, v46, v45
	v_div_fmas_f32 v33, v33, v44, v46
	v_div_fixup_f32 v42, v33, v42, 1.0
	v_div_scale_f32 v33, s[20:21], v39, v39, 1.0
	v_rcp_f32_e32 v44, v33
	s_nop 0
	v_fma_f32 v45, -v33, v44, 1.0
	v_fmac_f32_e32 v44, v45, v44
	v_div_scale_f32 v45, vcc, 1.0, v39, 1.0
	v_mul_f32_e32 v46, v45, v44
	v_fma_f32 v47, -v33, v46, v45
	v_fmac_f32_e32 v46, v47, v44
	v_fma_f32 v33, -v33, v46, v45
	v_div_fmas_f32 v33, v33, v44, v46
	v_div_fixup_f32 v39, v33, v39, 1.0
	v_div_scale_f32 v33, s[20:21], v38, v38, 1.0
	v_rcp_f32_e32 v44, v33
	s_nop 0
	v_fma_f32 v45, -v33, v44, 1.0
	v_fmac_f32_e32 v44, v45, v44
	v_div_scale_f32 v45, vcc, 1.0, v38, 1.0
	v_mul_f32_e32 v46, v45, v44
	v_fma_f32 v47, -v33, v46, v45
	v_fmac_f32_e32 v46, v47, v44
	v_fma_f32 v33, -v33, v46, v45
	v_div_fmas_f32 v33, v33, v44, v46
	v_div_fixup_f32 v38, v33, v38, 1.0
	v_pk_mul_f32 v[36:37], v[38:39], v[36:37]
	v_pk_mul_f32 v[38:39], v[42:43], v[40:41]
	v_pk_mul_f32 v[20:21], v[36:37], v[20:21]
	v_pk_mul_f32 v[22:23], v[38:39], v[22:23]
	v_mov_b32_e32 v36, v236
	v_mov_b32_e32 v37, v237
	v_mov_b32_e32 v38, v238
	v_mov_b32_e32 v39, v239
	v_pk_mul_f32 v[24:25], v[32:33], v[24:25] op_sel_hi:[0,1]
	v_pk_mul_f32 v[26:27], v[32:33], v[26:27] op_sel_hi:[0,1]
	v_lshlrev_b32_e32 v40, 16, v107
	v_and_b32_e32 v41, 0xffff0000, v107
	s_waitcnt vmcnt(0)
	v_pk_mul_f32 v[24:25], v[36:37], v[24:25]
	v_lshlrev_b32_e32 v36, 16, v106
	v_and_b32_e32 v37, 0xffff0000, v106
	v_mul_f32_e32 v33, 0xbfb8aa3b, v36
	v_pk_mul_f32 v[26:27], v[38:39], v[26:27]
	v_exp_f32_e32 v38, v33
	v_mul_f32_e32 v33, 0xbfb8aa3b, v37
	v_exp_f32_e32 v39, v33
	v_mul_f32_e32 v33, 0xbfb8aa3b, v40
	v_exp_f32_e32 v42, v33
	v_mul_f32_e32 v33, 0xbfb8aa3b, v41
	v_exp_f32_e32 v43, v33
	v_pk_add_f32 v[38:39], v[38:39], 1.0 op_sel_hi:[1,0]
	v_pk_add_f32 v[42:43], v[42:43], 1.0 op_sel_hi:[1,0]
	s_nop 0
	v_div_scale_f32 v33, s[20:21], v43, v43, 1.0
	v_rcp_f32_e32 v44, v33
	s_nop 0
	v_fma_f32 v45, -v33, v44, 1.0
	v_fmac_f32_e32 v44, v45, v44
	v_div_scale_f32 v45, vcc, 1.0, v43, 1.0
	v_mul_f32_e32 v46, v45, v44
	v_fma_f32 v47, -v33, v46, v45
	v_fmac_f32_e32 v46, v47, v44
	v_fma_f32 v33, -v33, v46, v45
	v_div_fmas_f32 v33, v33, v44, v46
	v_div_fixup_f32 v43, v33, v43, 1.0
	v_div_scale_f32 v33, s[20:21], v42, v42, 1.0
	v_rcp_f32_e32 v44, v33
	s_nop 0
	v_fma_f32 v45, -v33, v44, 1.0
	v_fmac_f32_e32 v44, v45, v44
	v_div_scale_f32 v45, vcc, 1.0, v42, 1.0
	v_mul_f32_e32 v46, v45, v44
	v_fma_f32 v47, -v33, v46, v45
	v_fmac_f32_e32 v46, v47, v44
	v_fma_f32 v33, -v33, v46, v45
	v_div_fmas_f32 v33, v33, v44, v46
	v_div_fixup_f32 v42, v33, v42, 1.0
	v_div_scale_f32 v33, s[20:21], v39, v39, 1.0
	v_rcp_f32_e32 v44, v33
	s_nop 0
	v_fma_f32 v45, -v33, v44, 1.0
	v_fmac_f32_e32 v44, v45, v44
	v_div_scale_f32 v45, vcc, 1.0, v39, 1.0
	v_mul_f32_e32 v46, v45, v44
	v_fma_f32 v47, -v33, v46, v45
	v_fmac_f32_e32 v46, v47, v44
	v_fma_f32 v33, -v33, v46, v45
	v_div_fmas_f32 v33, v33, v44, v46
	v_div_fixup_f32 v39, v33, v39, 1.0
	v_div_scale_f32 v33, s[20:21], v38, v38, 1.0
	v_rcp_f32_e32 v44, v33
	s_nop 0
	v_fma_f32 v45, -v33, v44, 1.0
	v_fmac_f32_e32 v44, v45, v44
	v_div_scale_f32 v45, vcc, 1.0, v38, 1.0
	v_mul_f32_e32 v46, v45, v44
	v_fma_f32 v47, -v33, v46, v45
	v_fmac_f32_e32 v46, v47, v44
	v_fma_f32 v33, -v33, v46, v45
	v_div_fmas_f32 v33, v33, v44, v46
	v_div_fixup_f32 v38, v33, v38, 1.0
	v_pk_mul_f32 v[36:37], v[38:39], v[36:37]
	v_pk_mul_f32 v[30:31], v[32:33], v[30:31] op_sel_hi:[0,1]
	v_pk_mul_f32 v[24:25], v[36:37], v[24:25]
	v_mov_b32_e32 v34, v240
	v_mov_b32_e32 v35, v241
	v_mov_b32_e32 v36, v242
	v_mov_b32_e32 v37, v243
	v_pk_mul_f32 v[38:39], v[42:43], v[40:41]
	v_pk_mul_f32 v[28:29], v[32:33], v[28:29] op_sel_hi:[0,1]
	v_pk_mul_f32 v[26:27], v[38:39], v[26:27]
	v_lshlrev_b32_e32 v32, 16, v104
	v_and_b32_e32 v33, 0xffff0000, v104
	s_waitcnt vmcnt(0)
; #define LAS __attribute__((address_space(3)))
; __device__ __forceinline__ float bflo(unsigned w) { return __uint_as_float(w << 16); }
; __device__ __forceinline__ float bfhi(unsigned w) { return __uint_as_float(w & 0xffff0000u); }
; __device__ __forceinline__ float sigmoidf_(float x) { return 1.0f / (1.0f + __expf(-x)); }
; __global__ void __launch_bounds__(512, 2) mega_fwd(Args a) {
;     ...
;                     for (int dt = 0; dt < 2; ++dt)
; #pragma unroll
;                         for (int rg = 0; rg < 4; ++rg) {
;                             const int d0 = 32 * dt + 8 * rg + 4 * hi;
;                             const u32x2 gt2 = gtv[dt * 4 + rg]; const f32x4 gn = *(const f32x4*)(ng + d0);
;                             const float g0 = bflo(gt2.x), g1 = bfhi(gt2.x), g2 = bflo(gt2.y), g3 = bfhi(gt2.y);
;                             f32x4 y;
;                             if (dt == 0) { y.x = O0[4 * rg]; y.y = O0[4 * rg + 1]; y.z = O0[4 * rg + 2]; y.w = O0[4 * rg + 3]; }
;                             else { y.x = O1[4 * rg]; y.y = O1[4 * rg + 1]; y.z = O1[4 * rg + 2]; y.w = O1[4 * rg + 3]; }
;                             y = y * rs * gn;
;                             y.x *= g0 * sigmoidf_(g0); y.y *= g1 * sigmoidf_(g1); y.z *= g2 * sigmoidf_(g2); y.w *= g3 * sigmoidf_(g3);
;                             yv[dt * 4 + rg] = y;
;                         }
;                     if (dir == 1) {
; #pragma unroll
;                         for (int dt = 0; dt < 2; ++dt)
; #pragma unroll
;                             for (int rg = 0; rg < 4; ++rg) *(LAS f32x4*)(YX + qi * 64 + 32 * dt + 8 * rg + 4 * hi) = yv[dt * 4 + rg];
;                     }
	v_pk_mul_f32 v[30:31], v[36:37], v[30:31]
	v_lshlrev_b32_e32 v36, 16, v105
	v_and_b32_e32 v37, 0xffff0000, v105
	v_mul_f32_e32 v38, 0xbfb8aa3b, v36
	v_mul_f32_e32 v39, 0xbfb8aa3b, v37
	v_exp_f32_e32 v38, v38
	v_exp_f32_e32 v39, v39
	v_pk_mul_f32 v[28:29], v[34:35], v[28:29]
	v_mul_f32_e32 v34, 0xbfb8aa3b, v32
	v_mul_f32_e32 v35, 0xbfb8aa3b, v33
	v_pk_add_f32 v[38:39], v[38:39], 1.0 op_sel_hi:[1,0]
	v_exp_f32_e32 v34, v34
	v_div_scale_f32 v40, s[20:21], v39, v39, 1.0
	v_rcp_f32_e32 v41, v40
	v_exp_f32_e32 v35, v35
	v_fma_f32 v42, -v40, v41, 1.0
	v_fmac_f32_e32 v41, v42, v41
	v_div_scale_f32 v42, vcc, 1.0, v39, 1.0
	v_mul_f32_e32 v43, v42, v41
	v_fma_f32 v44, -v40, v43, v42
	v_fmac_f32_e32 v43, v44, v41
	v_fma_f32 v40, -v40, v43, v42
	v_div_fmas_f32 v40, v40, v41, v43
	v_div_fixup_f32 v39, v40, v39, 1.0
	v_div_scale_f32 v40, s[20:21], v38, v38, 1.0
	v_rcp_f32_e32 v41, v40
	v_pk_add_f32 v[34:35], v[34:35], 1.0 op_sel_hi:[1,0]
	v_fma_f32 v42, -v40, v41, 1.0
	v_fmac_f32_e32 v41, v42, v41
	v_div_scale_f32 v42, vcc, 1.0, v38, 1.0
	v_mul_f32_e32 v43, v42, v41
	v_fma_f32 v44, -v40, v43, v42
	v_fmac_f32_e32 v43, v44, v41
	v_fma_f32 v40, -v40, v43, v42
	v_div_fmas_f32 v40, v40, v41, v43
	v_div_fixup_f32 v38, v40, v38, 1.0
	v_div_scale_f32 v40, s[20:21], v35, v35, 1.0
	v_rcp_f32_e32 v41, v40
	s_nop 0
	v_fma_f32 v42, -v40, v41, 1.0
	v_fmac_f32_e32 v41, v42, v41
	v_div_scale_f32 v42, vcc, 1.0, v35, 1.0
	v_mul_f32_e32 v43, v42, v41
	v_fma_f32 v44, -v40, v43, v42
	v_fmac_f32_e32 v43, v44, v41
	v_fma_f32 v40, -v40, v43, v42
	v_div_fmas_f32 v40, v40, v41, v43
	v_div_fixup_f32 v35, v40, v35, 1.0
	v_div_scale_f32 v40, s[20:21], v34, v34, 1.0
	v_rcp_f32_e32 v41, v40
	v_readlane_b32 s20, v253, 7
	v_readlane_b32 s21, v253, 8
	v_fma_f32 v42, -v40, v41, 1.0
	v_fmac_f32_e32 v41, v42, v41
	v_div_scale_f32 v42, vcc, 1.0, v34, 1.0
	v_mul_f32_e32 v43, v42, v41
	v_fma_f32 v44, -v40, v43, v42
	v_fmac_f32_e32 v43, v44, v41
	v_fma_f32 v40, -v40, v43, v42
	v_div_fmas_f32 v40, v40, v41, v43
	v_div_fixup_f32 v34, v40, v34, 1.0
	v_pk_mul_f32 v[32:33], v[34:35], v[32:33]
	v_pk_mul_f32 v[34:35], v[38:39], v[36:37]
	v_pk_mul_f32 v[28:29], v[32:33], v[28:29]
	v_pk_mul_f32 v[30:31], v[34:35], v[30:31]
	s_andn2_b64 vcc, exec, s[20:21]
	s_cbranch_vccnz .LBB0_614
	ds_write_b128 v212, v[0:3] offset:17408
	ds_write_b128 v212, v[4:7] offset:17440
	ds_write_b128 v212, v[8:11] offset:17472
	ds_write_b128 v212, v[12:15] offset:17504
	ds_write_b128 v212, v[16:19] offset:17536
	ds_write_b128 v212, v[20:23] offset:17568
	ds_write_b128 v212, v[24:27] offset:17600
	ds_write_b128 v212, v[28:31] offset:17632
